# hg_norm and nsa_prep row passes rewritten: wide 16-B lane mapping, all rows loads in flight, DPP reductions
# speedup vs baseline: 1.0615x; 1.0065x over previous
.LBB0_275:
	s_or_b64 exec, exec, s[2:3]
	s_add_i32 s3, 0, 0x23fa8
	s_mov_b32 s2, -1
	v_mov_b32_e32 v0, s3
	s_barrier
	ds_read_b64 v[0:1], v0
	v_mbcnt_lo_u32_b32 v4, s2, 0
	v_mbcnt_hi_u32_b32 v4, s2, v4
	s_waitcnt lgkmcnt(0)
	v_readfirstlane_b32 s11, v0
	v_readfirstlane_b32 s20, v1
	s_add_u32 s21, s11, 0x4800000
	s_addc_u32 s24, s20, 0
	s_add_i32 s3, 0, 0x23f10
	v_mov_b32_e32 v0, s3
	s_add_i32 s3, 0, 0x23f48
	ds_read_b64 v[6:7], v0
	v_mov_b32_e32 v0, s3
	ds_read2_b64 v[0:3], v0 offset1:1
	s_andn2_b64 vcc, exec, s[0:1]
	s_waitcnt lgkmcnt(1)
	v_readfirstlane_b32 s25, v6
	v_readfirstlane_b32 s26, v7
	s_waitcnt lgkmcnt(0)
	v_readfirstlane_b32 s2, v0
	v_cndmask_b32_e64 v0, 0, 1, s[0:1]
	v_cmp_ne_u32_e64 s[6:7], 1, v0
	v_readfirstlane_b32 s3, v1
	v_mov_b32_e32 v1, 0
	v_readfirstlane_b32 s4, v2
	v_readfirstlane_b32 s5, v3
	v_writelane_b32 v247, s6, 12
	v_lshlrev_b32_e32 v0, 1, v4
	s_nop 0
	v_writelane_b32 v247, s7, 13
	s_cbranch_vccnz .LBB0_278
	s_cmpk_lg_i32 s76, 0x100
	s_cbranch_scc1 .Lnsp_generic
	s_mul_i32 s16, s84, 0x1c00
	s_add_u32 s0, s11, s16
	s_addc_u32 s1, s20, 0
	s_add_u32 s0, s0, 0x4801000
	s_addc_u32 s1, s1, 0
	s_lshl_b32 s16, s84, 7
	s_add_u32 s12, s11, s16
	s_addc_u32 s13, s20, 0
	s_add_u32 s6, s12, 0xb800000
	s_addc_u32 s7, s13, 0
	s_lshl_b32 s16, s84, 2
	s_add_u32 s14, s25, s16
	s_addc_u32 s15, s26, 0
	s_mov_b32 s10, 0x3c800000
	v_and_b32_e32 v9, 7, v4
	v_lshlrev_b32_e32 v5, 4, v4
	v_lshrrev_b32_e32 v13, 3, v4
	v_lshlrev_b32_e32 v7, 18, v13
	v_lshl_add_u32 v7, v9, 4, v7
	v_lshlrev_b32_e32 v14, 13, v13
	global_load_dword v11, v14, s[14:15]
	v_lshlrev_b32_e32 v14, 5, v9
	global_load_dwordx4 v[16:19], v14, s[2:3]
	global_load_dwordx4 v[20:23], v14, s[2:3] offset:16
	v_lshrrev_b32_e32 v8, 4, v4
	v_add_u32_e32 v10, -1, v8
	v_max_i32_e32 v10, 0, v10
	v_lshl_add_u32 v10, v10, 8, v14
	global_load_dwordx4 v[24:27], v10, s[4:5]
	global_load_dwordx4 v[28:31], v10, s[4:5] offset:16
	v_cmp_lt_u32_e64 s[16:17], 47, v4
	v_add_u32_e32 v6, 0x400, v5
	v_add_u32_e32 v14, 0x500, v5
	s_nop 0
	v_cndmask_b32_e64 v6, v6, v14, s[16:17]
	global_load_dwordx4 v[48:51], v5, s[0:1]
	global_load_dwordx4 v[52:55], v6, s[0:1]
	s_add_u32 s0, s0, 0xe00000
	s_addc_u32 s1, s1, 0
	global_load_dwordx4 v[56:59], v5, s[0:1]
	global_load_dwordx4 v[60:63], v6, s[0:1]
	s_add_u32 s0, s0, 0xe00000
	s_addc_u32 s1, s1, 0
	global_load_dwordx4 v[64:67], v5, s[0:1]
	global_load_dwordx4 v[68:71], v6, s[0:1]
	s_add_u32 s0, s0, 0xe00000
	s_addc_u32 s1, s1, 0
	global_load_dwordx4 v[72:75], v5, s[0:1]
	global_load_dwordx4 v[76:79], v6, s[0:1]
	s_add_u32 s0, s0, 0xe00000
	s_addc_u32 s1, s1, 0
	global_load_dwordx4 v[80:83], v5, s[0:1]
	global_load_dwordx4 v[84:87], v6, s[0:1]
	s_add_u32 s0, s0, 0xe00000
	s_addc_u32 s1, s1, 0
	global_load_dwordx4 v[88:91], v5, s[0:1]
	global_load_dwordx4 v[92:95], v6, s[0:1]
	s_add_u32 s0, s0, 0xe00000
	s_addc_u32 s1, s1, 0
	global_load_dwordx4 v[96:99], v5, s[0:1]
	global_load_dwordx4 v[100:103], v6, s[0:1]
	s_add_u32 s0, s0, 0xe00000
	s_addc_u32 s1, s1, 0
	global_load_dwordx4 v[104:107], v5, s[0:1]
	global_load_dwordx4 v[108:111], v6, s[0:1]
	s_add_u32 s0, s0, 0xe00000
	s_addc_u32 s1, s1, 0
	v_cmp_eq_u32_e64 s[16:17], 3, v8
	v_mul_u32_u24_e32 v14, 5, v8
	v_add_u32_e32 v14, 0xc8, v14
	v_cndmask_b32_e64 v10, 0, 5, s[16:17]
	v_add_u32_e32 v14, v14, v10
	v_lshlrev_b32_e32 v14, 20, v14
	v_and_b32_e32 v13, 1, v13
	v_lshl_add_u32 v14, v13, 18, v14
	v_cmp_eq_u32_e64 s[18:19], 1, v8
	v_lshl_add_u32 v8, v9, 4, v14
	v_cmp_eq_u32_e64 s[16:17], 0, v9
	v_mov_b32_e32 v10, 0
	v_mov_b32_e32 v15, 0x358637bd
	v_cndmask_b32_e64 v10, v10, -1.0, s[16:17]
	v_cmp_eq_u32_e64 s[16:17], 1, v9
	s_nop 1
	v_cndmask_b32_e64 v10, v10, 1.0, s[16:17]
	v_mov_b32_e32 v13, 1.0
	v_cmp_eq_u32_e32 vcc, 1, v9
	v_mov_b32_e32 v14, 0x3e4693af
	s_nop 0
	v_cndmask_b32_e32 v13, v13, v14, vcc
	v_cmp_eq_u32_e32 vcc, 2, v9
	v_mov_b32_e32 v14, 0x3d1a08c8
	s_nop 0
	v_cndmask_b32_e32 v13, v13, v14, vcc
	v_cmp_eq_u32_e32 vcc, 3, v9
	v_mov_b32_e32 v14, 0x3beef74e
	s_nop 0
	v_cndmask_b32_e32 v13, v13, v14, vcc
	v_cmp_eq_u32_e32 vcc, 4, v9
	v_mov_b32_e32 v14, 0x3ab95d22
	s_nop 0
	v_cndmask_b32_e32 v13, v13, v14, vcc
	v_cmp_eq_u32_e32 vcc, 5, v9
	v_mov_b32_e32 v14, 0x398fc8f8
	s_nop 0
	v_cndmask_b32_e32 v13, v13, v14, vcc
	v_cmp_eq_u32_e32 vcc, 6, v9
	v_mov_b32_e32 v14, 0x385f10c4
	s_nop 0
	v_cndmask_b32_e32 v13, v13, v14, vcc
	v_cmp_eq_u32_e32 vcc, 7, v9
	v_mov_b32_e32 v14, 0x372d07a7
	s_nop 0
	v_cndmask_b32_e32 v13, v13, v14, vcc
	s_waitcnt vmcnt(20)
	v_cvt_f32_i32_e32 v11, v11
	v_mul_f32_e32 v11, v13, v11
	v_mul_f32_e32 v14, 0.15915494, v11
	v_floor_f32_e32 v14, v14
	v_fma_f32 v14, v11, 0.15915494, -v14
	v_cos_f32_e32 v11, v14
	v_sin_f32_e32 v12, v14
	v_cmp_gt_u32_e32 vcc, 2, v9
	s_waitcnt vmcnt(16)
	s_waitcnt vmcnt(14)
	v_readlane_b32 s28, v11, 0
	v_readlane_b32 s38, v12, 0
	v_readlane_b32 s29, v11, 1
	v_readlane_b32 s39, v12, 1
	v_readlane_b32 s30, v11, 2
	v_readlane_b32 s40, v12, 2
	v_readlane_b32 s31, v11, 3
	v_readlane_b32 s41, v12, 3
	v_readlane_b32 s34, v11, 4
	v_readlane_b32 s42, v12, 4
	v_readlane_b32 s35, v11, 5
	v_readlane_b32 s43, v12, 5
	v_readlane_b32 s36, v11, 6
	v_readlane_b32 s44, v12, 6
	v_readlane_b32 s37, v11, 7
	v_readlane_b32 s45, v12, 7
	v_mul_f32_e32 v32, s38, v10
	v_mul_f32_e32 v33, s39, v10
	v_mul_f32_e32 v34, s40, v10
	v_mul_f32_e32 v35, s41, v10
	v_mul_f32_e32 v36, s42, v10
	v_mul_f32_e32 v37, s43, v10
	v_mul_f32_e32 v38, s44, v10
	v_mul_f32_e32 v39, s45, v10
	v_lshlrev_b32_e32 v112, 16, v48
	v_and_b32_e32 v113, 0xffff0000, v48
	v_lshlrev_b32_e32 v114, 16, v49
	v_and_b32_e32 v115, 0xffff0000, v49
	v_lshlrev_b32_e32 v116, 16, v50
	v_and_b32_e32 v117, 0xffff0000, v50
	v_lshlrev_b32_e32 v118, 16, v51
	v_and_b32_e32 v119, 0xffff0000, v51
	v_mul_f32_e32 v140, v112, v112
	v_mul_f32_e32 v141, v113, v113
	v_fmac_f32_e32 v140, v114, v114
	v_fmac_f32_e32 v141, v115, v115
	v_fmac_f32_e32 v140, v116, v116
	v_fmac_f32_e32 v141, v117, v117
	v_fmac_f32_e32 v140, v118, v118
	v_fmac_f32_e32 v141, v119, v119
	v_add_f32_e32 v140, v140, v141
	s_nop 1
	v_add_f32_dpp v140, v140, v140 quad_perm:[1,0,3,2] row_mask:0xf bank_mask:0xf bound_ctrl:1
	s_nop 1
	v_add_f32_dpp v140, v140, v140 quad_perm:[2,3,0,1] row_mask:0xf bank_mask:0xf bound_ctrl:1
	s_nop 1
	v_add_f32_dpp v140, v140, v140 row_half_mirror row_mask:0xf bank_mask:0xf bound_ctrl:1
	v_fma_f32 v141, v140, s10, v15
	v_rsq_f32_e32 v141, v141
	s_nop 0
	v_mul_f32_e32 v112, v112, v141
	v_mul_f32_e32 v113, v113, v141
	v_mul_f32_e32 v114, v114, v141
	v_mul_f32_e32 v115, v115, v141
	v_mul_f32_e32 v116, v116, v141
	v_mul_f32_e32 v117, v117, v141
	v_mul_f32_e32 v118, v118, v141
	v_mul_f32_e32 v119, v119, v141
	v_mul_f32_e32 v112, v112, v16
	v_mul_f32_e32 v113, v113, v17
	v_mul_f32_e32 v114, v114, v18
	v_mul_f32_e32 v115, v115, v19
	v_mul_f32_e32 v116, v116, v20
	v_mul_f32_e32 v117, v117, v21
	v_mul_f32_e32 v118, v118, v22
	v_mul_f32_e32 v119, v119, v23
	v_mov_b32_dpp v120, v112 quad_perm:[1,0,3,2] row_mask:0xf bank_mask:0xf
	v_mov_b32_dpp v121, v113 quad_perm:[1,0,3,2] row_mask:0xf bank_mask:0xf
	v_mov_b32_dpp v122, v114 quad_perm:[1,0,3,2] row_mask:0xf bank_mask:0xf
	v_mov_b32_dpp v123, v115 quad_perm:[1,0,3,2] row_mask:0xf bank_mask:0xf
	v_mov_b32_dpp v124, v116 quad_perm:[1,0,3,2] row_mask:0xf bank_mask:0xf
	v_mov_b32_dpp v125, v117 quad_perm:[1,0,3,2] row_mask:0xf bank_mask:0xf
	v_mov_b32_dpp v126, v118 quad_perm:[1,0,3,2] row_mask:0xf bank_mask:0xf
	v_mov_b32_dpp v127, v119 quad_perm:[1,0,3,2] row_mask:0xf bank_mask:0xf
	v_mul_f32_e32 v128, s28, v112
	v_mul_f32_e32 v129, s29, v113
	v_mul_f32_e32 v130, s30, v114
	v_mul_f32_e32 v131, s31, v115
	v_mul_f32_e32 v132, s34, v116
	v_mul_f32_e32 v133, s35, v117
	v_mul_f32_e32 v134, s36, v118
	v_mul_f32_e32 v135, s37, v119
	v_fmac_f32_e32 v128, v32, v120
	v_fmac_f32_e32 v129, v33, v121
	v_fmac_f32_e32 v130, v34, v122
	v_fmac_f32_e32 v131, v35, v123
	v_fmac_f32_e32 v132, v36, v124
	v_fmac_f32_e32 v133, v37, v125
	v_fmac_f32_e32 v134, v38, v126
	v_fmac_f32_e32 v135, v39, v127
	v_cndmask_b32_e32 v112, v112, v128, vcc
	v_cndmask_b32_e32 v113, v113, v129, vcc
	v_cndmask_b32_e32 v114, v114, v130, vcc
	v_cndmask_b32_e32 v115, v115, v131, vcc
	v_cndmask_b32_e32 v116, v116, v132, vcc
	v_cndmask_b32_e32 v117, v117, v133, vcc
	v_cndmask_b32_e32 v118, v118, v134, vcc
	v_cndmask_b32_e32 v119, v119, v135, vcc
	v_mul_f32_e32 v112, 0x3e38aa3b, v112
	v_mul_f32_e32 v113, 0x3e38aa3b, v113
	v_mul_f32_e32 v114, 0x3e38aa3b, v114
	v_mul_f32_e32 v115, 0x3e38aa3b, v115
	v_mul_f32_e32 v116, 0x3e38aa3b, v116
	v_mul_f32_e32 v117, 0x3e38aa3b, v117
	v_mul_f32_e32 v118, 0x3e38aa3b, v118
	v_mul_f32_e32 v119, 0x3e38aa3b, v119
	v_cvt_pk_bf16_f32 v136, v112, v113
	v_cvt_pk_bf16_f32 v137, v114, v115
	v_cvt_pk_bf16_f32 v138, v116, v117
	v_cvt_pk_bf16_f32 v139, v118, v119
	global_store_dwordx4 v7, v[136:139], s[6:7]
	s_nop 1
	v_lshlrev_b32_e32 v112, 16, v52
	v_and_b32_e32 v113, 0xffff0000, v52
	v_lshlrev_b32_e32 v114, 16, v53
	v_and_b32_e32 v115, 0xffff0000, v53
	v_lshlrev_b32_e32 v116, 16, v54
	v_and_b32_e32 v117, 0xffff0000, v54
	v_lshlrev_b32_e32 v118, 16, v55
	v_and_b32_e32 v119, 0xffff0000, v55
	v_mul_f32_e32 v140, v112, v112
	v_mul_f32_e32 v141, v113, v113
	v_fmac_f32_e32 v140, v114, v114
	v_fmac_f32_e32 v141, v115, v115
	v_fmac_f32_e32 v140, v116, v116
	v_fmac_f32_e32 v141, v117, v117
	v_fmac_f32_e32 v140, v118, v118
	v_fmac_f32_e32 v141, v119, v119
	v_add_f32_e32 v140, v140, v141
	s_nop 1
	v_add_f32_dpp v140, v140, v140 quad_perm:[1,0,3,2] row_mask:0xf bank_mask:0xf bound_ctrl:1
	s_nop 1
	v_add_f32_dpp v140, v140, v140 quad_perm:[2,3,0,1] row_mask:0xf bank_mask:0xf bound_ctrl:1
	s_nop 1
	v_add_f32_dpp v140, v140, v140 row_half_mirror row_mask:0xf bank_mask:0xf bound_ctrl:1
	v_fma_f32 v141, v140, s10, v15
	v_rsq_f32_e32 v141, v141
	s_nop 0
	v_mul_f32_e32 v112, v112, v141
	v_mul_f32_e32 v113, v113, v141
	v_mul_f32_e32 v114, v114, v141
	v_mul_f32_e32 v115, v115, v141
	v_mul_f32_e32 v116, v116, v141
	v_mul_f32_e32 v117, v117, v141
	v_mul_f32_e32 v118, v118, v141
	v_mul_f32_e32 v119, v119, v141
	v_mul_f32_e32 v112, v112, v24
	v_mul_f32_e32 v113, v113, v25
	v_mul_f32_e32 v114, v114, v26
	v_mul_f32_e32 v115, v115, v27
	v_mul_f32_e32 v116, v116, v28
	v_mul_f32_e32 v117, v117, v29
	v_mul_f32_e32 v118, v118, v30
	v_mul_f32_e32 v119, v119, v31
	v_mov_b32_dpp v120, v112 quad_perm:[1,0,3,2] row_mask:0xf bank_mask:0xf
	v_mov_b32_dpp v121, v113 quad_perm:[1,0,3,2] row_mask:0xf bank_mask:0xf
	v_mov_b32_dpp v122, v114 quad_perm:[1,0,3,2] row_mask:0xf bank_mask:0xf
	v_mov_b32_dpp v123, v115 quad_perm:[1,0,3,2] row_mask:0xf bank_mask:0xf
	v_mov_b32_dpp v124, v116 quad_perm:[1,0,3,2] row_mask:0xf bank_mask:0xf
	v_mov_b32_dpp v125, v117 quad_perm:[1,0,3,2] row_mask:0xf bank_mask:0xf
	v_mov_b32_dpp v126, v118 quad_perm:[1,0,3,2] row_mask:0xf bank_mask:0xf
	v_mov_b32_dpp v127, v119 quad_perm:[1,0,3,2] row_mask:0xf bank_mask:0xf
	v_mul_f32_e32 v128, s28, v112
	v_mul_f32_e32 v129, s29, v113
	v_mul_f32_e32 v130, s30, v114
	v_mul_f32_e32 v131, s31, v115
	v_mul_f32_e32 v132, s34, v116
	v_mul_f32_e32 v133, s35, v117
	v_mul_f32_e32 v134, s36, v118
	v_mul_f32_e32 v135, s37, v119
	v_fmac_f32_e32 v128, v32, v120
	v_fmac_f32_e32 v129, v33, v121
	v_fmac_f32_e32 v130, v34, v122
	v_fmac_f32_e32 v131, v35, v123
	v_fmac_f32_e32 v132, v36, v124
	v_fmac_f32_e32 v133, v37, v125
	v_fmac_f32_e32 v134, v38, v126
	v_fmac_f32_e32 v135, v39, v127
	v_cndmask_b32_e32 v112, v112, v128, vcc
	v_cndmask_b32_e32 v113, v113, v129, vcc
	v_cndmask_b32_e32 v114, v114, v130, vcc
	v_cndmask_b32_e32 v115, v115, v131, vcc
	v_cndmask_b32_e32 v116, v116, v132, vcc
	v_cndmask_b32_e32 v117, v117, v133, vcc
	v_cndmask_b32_e32 v118, v118, v134, vcc
	v_cndmask_b32_e32 v119, v119, v135, vcc
	v_cvt_pk_bf16_f32 v136, v112, v113
	v_cvt_pk_bf16_f32 v137, v114, v115
	v_cvt_pk_bf16_f32 v138, v116, v117
	v_cvt_pk_bf16_f32 v139, v118, v119
	v_cndmask_b32_e64 v136, v136, v52, s[18:19]
	v_cndmask_b32_e64 v137, v137, v53, s[18:19]
	v_cndmask_b32_e64 v138, v138, v54, s[18:19]
	v_cndmask_b32_e64 v139, v139, v55, s[18:19]
	global_store_dwordx4 v8, v[136:139], s[12:13]
	s_add_u32 s6, s6, 0x200000
	s_addc_u32 s7, s7, 0
	s_add_u32 s12, s12, 0x80000
	s_addc_u32 s13, s13, 0
	s_waitcnt vmcnt(14)
	v_readlane_b32 s28, v11, 8
	v_readlane_b32 s38, v12, 8
	v_readlane_b32 s29, v11, 9
	v_readlane_b32 s39, v12, 9
	v_readlane_b32 s30, v11, 10
	v_readlane_b32 s40, v12, 10
	v_readlane_b32 s31, v11, 11
	v_readlane_b32 s41, v12, 11
	v_readlane_b32 s34, v11, 12
	v_readlane_b32 s42, v12, 12
	v_readlane_b32 s35, v11, 13
	v_readlane_b32 s43, v12, 13
	v_readlane_b32 s36, v11, 14
	v_readlane_b32 s44, v12, 14
	v_readlane_b32 s37, v11, 15
	v_readlane_b32 s45, v12, 15
	v_mul_f32_e32 v32, s38, v10
	v_mul_f32_e32 v33, s39, v10
	v_mul_f32_e32 v34, s40, v10
	v_mul_f32_e32 v35, s41, v10
	v_mul_f32_e32 v36, s42, v10
	v_mul_f32_e32 v37, s43, v10
	v_mul_f32_e32 v38, s44, v10
	v_mul_f32_e32 v39, s45, v10
	v_lshlrev_b32_e32 v112, 16, v56
	v_and_b32_e32 v113, 0xffff0000, v56
	v_lshlrev_b32_e32 v114, 16, v57
	v_and_b32_e32 v115, 0xffff0000, v57
	v_lshlrev_b32_e32 v116, 16, v58
	v_and_b32_e32 v117, 0xffff0000, v58
	v_lshlrev_b32_e32 v118, 16, v59
	v_and_b32_e32 v119, 0xffff0000, v59
	v_mul_f32_e32 v140, v112, v112
	v_mul_f32_e32 v141, v113, v113
	v_fmac_f32_e32 v140, v114, v114
	v_fmac_f32_e32 v141, v115, v115
	v_fmac_f32_e32 v140, v116, v116
	v_fmac_f32_e32 v141, v117, v117
	v_fmac_f32_e32 v140, v118, v118
	v_fmac_f32_e32 v141, v119, v119
	v_add_f32_e32 v140, v140, v141
	s_nop 1
	v_add_f32_dpp v140, v140, v140 quad_perm:[1,0,3,2] row_mask:0xf bank_mask:0xf bound_ctrl:1
	s_nop 1
	v_add_f32_dpp v140, v140, v140 quad_perm:[2,3,0,1] row_mask:0xf bank_mask:0xf bound_ctrl:1
	s_nop 1
	v_add_f32_dpp v140, v140, v140 row_half_mirror row_mask:0xf bank_mask:0xf bound_ctrl:1
	v_fma_f32 v141, v140, s10, v15
	v_rsq_f32_e32 v141, v141
	s_nop 0
	v_mul_f32_e32 v112, v112, v141
	v_mul_f32_e32 v113, v113, v141
	v_mul_f32_e32 v114, v114, v141
	v_mul_f32_e32 v115, v115, v141
	v_mul_f32_e32 v116, v116, v141
	v_mul_f32_e32 v117, v117, v141
	v_mul_f32_e32 v118, v118, v141
	v_mul_f32_e32 v119, v119, v141
	v_mul_f32_e32 v112, v112, v16
	v_mul_f32_e32 v113, v113, v17
	v_mul_f32_e32 v114, v114, v18
	v_mul_f32_e32 v115, v115, v19
	v_mul_f32_e32 v116, v116, v20
	v_mul_f32_e32 v117, v117, v21
	v_mul_f32_e32 v118, v118, v22
	v_mul_f32_e32 v119, v119, v23
	v_mov_b32_dpp v120, v112 quad_perm:[1,0,3,2] row_mask:0xf bank_mask:0xf
	v_mov_b32_dpp v121, v113 quad_perm:[1,0,3,2] row_mask:0xf bank_mask:0xf
	v_mov_b32_dpp v122, v114 quad_perm:[1,0,3,2] row_mask:0xf bank_mask:0xf
	v_mov_b32_dpp v123, v115 quad_perm:[1,0,3,2] row_mask:0xf bank_mask:0xf
	v_mov_b32_dpp v124, v116 quad_perm:[1,0,3,2] row_mask:0xf bank_mask:0xf
	v_mov_b32_dpp v125, v117 quad_perm:[1,0,3,2] row_mask:0xf bank_mask:0xf
	v_mov_b32_dpp v126, v118 quad_perm:[1,0,3,2] row_mask:0xf bank_mask:0xf
	v_mov_b32_dpp v127, v119 quad_perm:[1,0,3,2] row_mask:0xf bank_mask:0xf
	v_mul_f32_e32 v128, s28, v112
	v_mul_f32_e32 v129, s29, v113
	v_mul_f32_e32 v130, s30, v114
	v_mul_f32_e32 v131, s31, v115
	v_mul_f32_e32 v132, s34, v116
	v_mul_f32_e32 v133, s35, v117
	v_mul_f32_e32 v134, s36, v118
	v_mul_f32_e32 v135, s37, v119
	v_fmac_f32_e32 v128, v32, v120
	v_fmac_f32_e32 v129, v33, v121
	v_fmac_f32_e32 v130, v34, v122
	v_fmac_f32_e32 v131, v35, v123
	v_fmac_f32_e32 v132, v36, v124
	v_fmac_f32_e32 v133, v37, v125
	v_fmac_f32_e32 v134, v38, v126
	v_fmac_f32_e32 v135, v39, v127
	v_cndmask_b32_e32 v112, v112, v128, vcc
	v_cndmask_b32_e32 v113, v113, v129, vcc
	v_cndmask_b32_e32 v114, v114, v130, vcc
	v_cndmask_b32_e32 v115, v115, v131, vcc
	v_cndmask_b32_e32 v116, v116, v132, vcc
	v_cndmask_b32_e32 v117, v117, v133, vcc
	v_cndmask_b32_e32 v118, v118, v134, vcc
	v_cndmask_b32_e32 v119, v119, v135, vcc
	v_mul_f32_e32 v112, 0x3e38aa3b, v112
	v_mul_f32_e32 v113, 0x3e38aa3b, v113
	v_mul_f32_e32 v114, 0x3e38aa3b, v114
	v_mul_f32_e32 v115, 0x3e38aa3b, v115
	v_mul_f32_e32 v116, 0x3e38aa3b, v116
	v_mul_f32_e32 v117, 0x3e38aa3b, v117
	v_mul_f32_e32 v118, 0x3e38aa3b, v118
	v_mul_f32_e32 v119, 0x3e38aa3b, v119
	v_cvt_pk_bf16_f32 v136, v112, v113
	v_cvt_pk_bf16_f32 v137, v114, v115
	v_cvt_pk_bf16_f32 v138, v116, v117
	v_cvt_pk_bf16_f32 v139, v118, v119
	global_store_dwordx4 v7, v[136:139], s[6:7]
	s_nop 1
	v_lshlrev_b32_e32 v112, 16, v60
	v_and_b32_e32 v113, 0xffff0000, v60
	v_lshlrev_b32_e32 v114, 16, v61
	v_and_b32_e32 v115, 0xffff0000, v61
	v_lshlrev_b32_e32 v116, 16, v62
	v_and_b32_e32 v117, 0xffff0000, v62
	v_lshlrev_b32_e32 v118, 16, v63
	v_and_b32_e32 v119, 0xffff0000, v63
	v_mul_f32_e32 v140, v112, v112
	v_mul_f32_e32 v141, v113, v113
	v_fmac_f32_e32 v140, v114, v114
	v_fmac_f32_e32 v141, v115, v115
	v_fmac_f32_e32 v140, v116, v116
	v_fmac_f32_e32 v141, v117, v117
	v_fmac_f32_e32 v140, v118, v118
	v_fmac_f32_e32 v141, v119, v119
	v_add_f32_e32 v140, v140, v141
	s_nop 1
	v_add_f32_dpp v140, v140, v140 quad_perm:[1,0,3,2] row_mask:0xf bank_mask:0xf bound_ctrl:1
	s_nop 1
	v_add_f32_dpp v140, v140, v140 quad_perm:[2,3,0,1] row_mask:0xf bank_mask:0xf bound_ctrl:1
	s_nop 1
	v_add_f32_dpp v140, v140, v140 row_half_mirror row_mask:0xf bank_mask:0xf bound_ctrl:1
	v_fma_f32 v141, v140, s10, v15
	v_rsq_f32_e32 v141, v141
	s_nop 0
	v_mul_f32_e32 v112, v112, v141
	v_mul_f32_e32 v113, v113, v141
	v_mul_f32_e32 v114, v114, v141
	v_mul_f32_e32 v115, v115, v141
	v_mul_f32_e32 v116, v116, v141
	v_mul_f32_e32 v117, v117, v141
	v_mul_f32_e32 v118, v118, v141
	v_mul_f32_e32 v119, v119, v141
	v_mul_f32_e32 v112, v112, v24
	v_mul_f32_e32 v113, v113, v25
	v_mul_f32_e32 v114, v114, v26
	v_mul_f32_e32 v115, v115, v27
	v_mul_f32_e32 v116, v116, v28
	v_mul_f32_e32 v117, v117, v29
	v_mul_f32_e32 v118, v118, v30
	v_mul_f32_e32 v119, v119, v31
	v_mov_b32_dpp v120, v112 quad_perm:[1,0,3,2] row_mask:0xf bank_mask:0xf
	v_mov_b32_dpp v121, v113 quad_perm:[1,0,3,2] row_mask:0xf bank_mask:0xf
	v_mov_b32_dpp v122, v114 quad_perm:[1,0,3,2] row_mask:0xf bank_mask:0xf
	v_mov_b32_dpp v123, v115 quad_perm:[1,0,3,2] row_mask:0xf bank_mask:0xf
	v_mov_b32_dpp v124, v116 quad_perm:[1,0,3,2] row_mask:0xf bank_mask:0xf
	v_mov_b32_dpp v125, v117 quad_perm:[1,0,3,2] row_mask:0xf bank_mask:0xf
	v_mov_b32_dpp v126, v118 quad_perm:[1,0,3,2] row_mask:0xf bank_mask:0xf
	v_mov_b32_dpp v127, v119 quad_perm:[1,0,3,2] row_mask:0xf bank_mask:0xf
	v_mul_f32_e32 v128, s28, v112
	v_mul_f32_e32 v129, s29, v113
	v_mul_f32_e32 v130, s30, v114
	v_mul_f32_e32 v131, s31, v115
	v_mul_f32_e32 v132, s34, v116
	v_mul_f32_e32 v133, s35, v117
	v_mul_f32_e32 v134, s36, v118
	v_mul_f32_e32 v135, s37, v119
	v_fmac_f32_e32 v128, v32, v120
	v_fmac_f32_e32 v129, v33, v121
	v_fmac_f32_e32 v130, v34, v122
	v_fmac_f32_e32 v131, v35, v123
	v_fmac_f32_e32 v132, v36, v124
	v_fmac_f32_e32 v133, v37, v125
	v_fmac_f32_e32 v134, v38, v126
	v_fmac_f32_e32 v135, v39, v127
	v_cndmask_b32_e32 v112, v112, v128, vcc
	v_cndmask_b32_e32 v113, v113, v129, vcc
	v_cndmask_b32_e32 v114, v114, v130, vcc
	v_cndmask_b32_e32 v115, v115, v131, vcc
	v_cndmask_b32_e32 v116, v116, v132, vcc
	v_cndmask_b32_e32 v117, v117, v133, vcc
	v_cndmask_b32_e32 v118, v118, v134, vcc
	v_cndmask_b32_e32 v119, v119, v135, vcc
	v_cvt_pk_bf16_f32 v136, v112, v113
	v_cvt_pk_bf16_f32 v137, v114, v115
	v_cvt_pk_bf16_f32 v138, v116, v117
	v_cvt_pk_bf16_f32 v139, v118, v119
	v_cndmask_b32_e64 v136, v136, v60, s[18:19]
	v_cndmask_b32_e64 v137, v137, v61, s[18:19]
	v_cndmask_b32_e64 v138, v138, v62, s[18:19]
	v_cndmask_b32_e64 v139, v139, v63, s[18:19]
	global_store_dwordx4 v8, v[136:139], s[12:13]
	s_add_u32 s6, s6, 0x200000
	s_addc_u32 s7, s7, 0
	s_add_u32 s12, s12, 0x80000
	s_addc_u32 s13, s13, 0
	s_waitcnt vmcnt(14)
	v_readlane_b32 s28, v11, 16
	v_readlane_b32 s38, v12, 16
	v_readlane_b32 s29, v11, 17
	v_readlane_b32 s39, v12, 17
	v_readlane_b32 s30, v11, 18
	v_readlane_b32 s40, v12, 18
	v_readlane_b32 s31, v11, 19
	v_readlane_b32 s41, v12, 19
	v_readlane_b32 s34, v11, 20
	v_readlane_b32 s42, v12, 20
	v_readlane_b32 s35, v11, 21
	v_readlane_b32 s43, v12, 21
	v_readlane_b32 s36, v11, 22
	v_readlane_b32 s44, v12, 22
	v_readlane_b32 s37, v11, 23
	v_readlane_b32 s45, v12, 23
	v_mul_f32_e32 v32, s38, v10
	v_mul_f32_e32 v33, s39, v10
	v_mul_f32_e32 v34, s40, v10
	v_mul_f32_e32 v35, s41, v10
	v_mul_f32_e32 v36, s42, v10
	v_mul_f32_e32 v37, s43, v10
	v_mul_f32_e32 v38, s44, v10
	v_mul_f32_e32 v39, s45, v10
	v_lshlrev_b32_e32 v112, 16, v64
	v_and_b32_e32 v113, 0xffff0000, v64
	v_lshlrev_b32_e32 v114, 16, v65
	v_and_b32_e32 v115, 0xffff0000, v65
	v_lshlrev_b32_e32 v116, 16, v66
	v_and_b32_e32 v117, 0xffff0000, v66
	v_lshlrev_b32_e32 v118, 16, v67
	v_and_b32_e32 v119, 0xffff0000, v67
	v_mul_f32_e32 v140, v112, v112
	v_mul_f32_e32 v141, v113, v113
	v_fmac_f32_e32 v140, v114, v114
	v_fmac_f32_e32 v141, v115, v115
	v_fmac_f32_e32 v140, v116, v116
	v_fmac_f32_e32 v141, v117, v117
	v_fmac_f32_e32 v140, v118, v118
	v_fmac_f32_e32 v141, v119, v119
	v_add_f32_e32 v140, v140, v141
	s_nop 1
	v_add_f32_dpp v140, v140, v140 quad_perm:[1,0,3,2] row_mask:0xf bank_mask:0xf bound_ctrl:1
	s_nop 1
	v_add_f32_dpp v140, v140, v140 quad_perm:[2,3,0,1] row_mask:0xf bank_mask:0xf bound_ctrl:1
	s_nop 1
	v_add_f32_dpp v140, v140, v140 row_half_mirror row_mask:0xf bank_mask:0xf bound_ctrl:1
	v_fma_f32 v141, v140, s10, v15
	v_rsq_f32_e32 v141, v141
	s_nop 0
	v_mul_f32_e32 v112, v112, v141
	v_mul_f32_e32 v113, v113, v141
	v_mul_f32_e32 v114, v114, v141
	v_mul_f32_e32 v115, v115, v141
	v_mul_f32_e32 v116, v116, v141
	v_mul_f32_e32 v117, v117, v141
	v_mul_f32_e32 v118, v118, v141
	v_mul_f32_e32 v119, v119, v141
	v_mul_f32_e32 v112, v112, v16
	v_mul_f32_e32 v113, v113, v17
	v_mul_f32_e32 v114, v114, v18
	v_mul_f32_e32 v115, v115, v19
	v_mul_f32_e32 v116, v116, v20
	v_mul_f32_e32 v117, v117, v21
	v_mul_f32_e32 v118, v118, v22
	v_mul_f32_e32 v119, v119, v23
	v_mov_b32_dpp v120, v112 quad_perm:[1,0,3,2] row_mask:0xf bank_mask:0xf
	v_mov_b32_dpp v121, v113 quad_perm:[1,0,3,2] row_mask:0xf bank_mask:0xf
	v_mov_b32_dpp v122, v114 quad_perm:[1,0,3,2] row_mask:0xf bank_mask:0xf
	v_mov_b32_dpp v123, v115 quad_perm:[1,0,3,2] row_mask:0xf bank_mask:0xf
	v_mov_b32_dpp v124, v116 quad_perm:[1,0,3,2] row_mask:0xf bank_mask:0xf
	v_mov_b32_dpp v125, v117 quad_perm:[1,0,3,2] row_mask:0xf bank_mask:0xf
	v_mov_b32_dpp v126, v118 quad_perm:[1,0,3,2] row_mask:0xf bank_mask:0xf
	v_mov_b32_dpp v127, v119 quad_perm:[1,0,3,2] row_mask:0xf bank_mask:0xf
	v_mul_f32_e32 v128, s28, v112
	v_mul_f32_e32 v129, s29, v113
	v_mul_f32_e32 v130, s30, v114
	v_mul_f32_e32 v131, s31, v115
	v_mul_f32_e32 v132, s34, v116
	v_mul_f32_e32 v133, s35, v117
	v_mul_f32_e32 v134, s36, v118
	v_mul_f32_e32 v135, s37, v119
	v_fmac_f32_e32 v128, v32, v120
	v_fmac_f32_e32 v129, v33, v121
	v_fmac_f32_e32 v130, v34, v122
	v_fmac_f32_e32 v131, v35, v123
	v_fmac_f32_e32 v132, v36, v124
	v_fmac_f32_e32 v133, v37, v125
	v_fmac_f32_e32 v134, v38, v126
	v_fmac_f32_e32 v135, v39, v127
	v_cndmask_b32_e32 v112, v112, v128, vcc
	v_cndmask_b32_e32 v113, v113, v129, vcc
	v_cndmask_b32_e32 v114, v114, v130, vcc
	v_cndmask_b32_e32 v115, v115, v131, vcc
	v_cndmask_b32_e32 v116, v116, v132, vcc
	v_cndmask_b32_e32 v117, v117, v133, vcc
	v_cndmask_b32_e32 v118, v118, v134, vcc
	v_cndmask_b32_e32 v119, v119, v135, vcc
	v_mul_f32_e32 v112, 0x3e38aa3b, v112
	v_mul_f32_e32 v113, 0x3e38aa3b, v113
	v_mul_f32_e32 v114, 0x3e38aa3b, v114
	v_mul_f32_e32 v115, 0x3e38aa3b, v115
	v_mul_f32_e32 v116, 0x3e38aa3b, v116
	v_mul_f32_e32 v117, 0x3e38aa3b, v117
	v_mul_f32_e32 v118, 0x3e38aa3b, v118
	v_mul_f32_e32 v119, 0x3e38aa3b, v119
	v_cvt_pk_bf16_f32 v136, v112, v113
	v_cvt_pk_bf16_f32 v137, v114, v115
	v_cvt_pk_bf16_f32 v138, v116, v117
	v_cvt_pk_bf16_f32 v139, v118, v119
	global_store_dwordx4 v7, v[136:139], s[6:7]
	s_nop 1
	v_lshlrev_b32_e32 v112, 16, v68
	v_and_b32_e32 v113, 0xffff0000, v68
	v_lshlrev_b32_e32 v114, 16, v69
	v_and_b32_e32 v115, 0xffff0000, v69
	v_lshlrev_b32_e32 v116, 16, v70
	v_and_b32_e32 v117, 0xffff0000, v70
	v_lshlrev_b32_e32 v118, 16, v71
	v_and_b32_e32 v119, 0xffff0000, v71
	v_mul_f32_e32 v140, v112, v112
	v_mul_f32_e32 v141, v113, v113
	v_fmac_f32_e32 v140, v114, v114
	v_fmac_f32_e32 v141, v115, v115
	v_fmac_f32_e32 v140, v116, v116
	v_fmac_f32_e32 v141, v117, v117
	v_fmac_f32_e32 v140, v118, v118
	v_fmac_f32_e32 v141, v119, v119
	v_add_f32_e32 v140, v140, v141
	s_nop 1
	v_add_f32_dpp v140, v140, v140 quad_perm:[1,0,3,2] row_mask:0xf bank_mask:0xf bound_ctrl:1
	s_nop 1
	v_add_f32_dpp v140, v140, v140 quad_perm:[2,3,0,1] row_mask:0xf bank_mask:0xf bound_ctrl:1
	s_nop 1
	v_add_f32_dpp v140, v140, v140 row_half_mirror row_mask:0xf bank_mask:0xf bound_ctrl:1
	v_fma_f32 v141, v140, s10, v15
	v_rsq_f32_e32 v141, v141
	s_nop 0
	v_mul_f32_e32 v112, v112, v141
	v_mul_f32_e32 v113, v113, v141
	v_mul_f32_e32 v114, v114, v141
	v_mul_f32_e32 v115, v115, v141
	v_mul_f32_e32 v116, v116, v141
	v_mul_f32_e32 v117, v117, v141
	v_mul_f32_e32 v118, v118, v141
	v_mul_f32_e32 v119, v119, v141
	v_mul_f32_e32 v112, v112, v24
	v_mul_f32_e32 v113, v113, v25
	v_mul_f32_e32 v114, v114, v26
	v_mul_f32_e32 v115, v115, v27
	v_mul_f32_e32 v116, v116, v28
	v_mul_f32_e32 v117, v117, v29
	v_mul_f32_e32 v118, v118, v30
	v_mul_f32_e32 v119, v119, v31
	v_mov_b32_dpp v120, v112 quad_perm:[1,0,3,2] row_mask:0xf bank_mask:0xf
	v_mov_b32_dpp v121, v113 quad_perm:[1,0,3,2] row_mask:0xf bank_mask:0xf
	v_mov_b32_dpp v122, v114 quad_perm:[1,0,3,2] row_mask:0xf bank_mask:0xf
	v_mov_b32_dpp v123, v115 quad_perm:[1,0,3,2] row_mask:0xf bank_mask:0xf
	v_mov_b32_dpp v124, v116 quad_perm:[1,0,3,2] row_mask:0xf bank_mask:0xf
	v_mov_b32_dpp v125, v117 quad_perm:[1,0,3,2] row_mask:0xf bank_mask:0xf
	v_mov_b32_dpp v126, v118 quad_perm:[1,0,3,2] row_mask:0xf bank_mask:0xf
	v_mov_b32_dpp v127, v119 quad_perm:[1,0,3,2] row_mask:0xf bank_mask:0xf
	v_mul_f32_e32 v128, s28, v112
	v_mul_f32_e32 v129, s29, v113
	v_mul_f32_e32 v130, s30, v114
	v_mul_f32_e32 v131, s31, v115
	v_mul_f32_e32 v132, s34, v116
	v_mul_f32_e32 v133, s35, v117
	v_mul_f32_e32 v134, s36, v118
	v_mul_f32_e32 v135, s37, v119
	v_fmac_f32_e32 v128, v32, v120
	v_fmac_f32_e32 v129, v33, v121
	v_fmac_f32_e32 v130, v34, v122
	v_fmac_f32_e32 v131, v35, v123
	v_fmac_f32_e32 v132, v36, v124
	v_fmac_f32_e32 v133, v37, v125
	v_fmac_f32_e32 v134, v38, v126
	v_fmac_f32_e32 v135, v39, v127
	v_cndmask_b32_e32 v112, v112, v128, vcc
	v_cndmask_b32_e32 v113, v113, v129, vcc
	v_cndmask_b32_e32 v114, v114, v130, vcc
	v_cndmask_b32_e32 v115, v115, v131, vcc
	v_cndmask_b32_e32 v116, v116, v132, vcc
	v_cndmask_b32_e32 v117, v117, v133, vcc
	v_cndmask_b32_e32 v118, v118, v134, vcc
	v_cndmask_b32_e32 v119, v119, v135, vcc
	v_cvt_pk_bf16_f32 v136, v112, v113
	v_cvt_pk_bf16_f32 v137, v114, v115
	v_cvt_pk_bf16_f32 v138, v116, v117
	v_cvt_pk_bf16_f32 v139, v118, v119
	v_cndmask_b32_e64 v136, v136, v68, s[18:19]
	v_cndmask_b32_e64 v137, v137, v69, s[18:19]
	v_cndmask_b32_e64 v138, v138, v70, s[18:19]
	v_cndmask_b32_e64 v139, v139, v71, s[18:19]
	global_store_dwordx4 v8, v[136:139], s[12:13]
	s_add_u32 s6, s6, 0x200000
	s_addc_u32 s7, s7, 0
	s_add_u32 s12, s12, 0x80000
	s_addc_u32 s13, s13, 0
	s_waitcnt vmcnt(14)
	v_readlane_b32 s28, v11, 24
	v_readlane_b32 s38, v12, 24
	v_readlane_b32 s29, v11, 25
	v_readlane_b32 s39, v12, 25
	v_readlane_b32 s30, v11, 26
	v_readlane_b32 s40, v12, 26
	v_readlane_b32 s31, v11, 27
	v_readlane_b32 s41, v12, 27
	v_readlane_b32 s34, v11, 28
	v_readlane_b32 s42, v12, 28
	v_readlane_b32 s35, v11, 29
	v_readlane_b32 s43, v12, 29
	v_readlane_b32 s36, v11, 30
	v_readlane_b32 s44, v12, 30
	v_readlane_b32 s37, v11, 31
	v_readlane_b32 s45, v12, 31
	v_mul_f32_e32 v32, s38, v10
	v_mul_f32_e32 v33, s39, v10
	v_mul_f32_e32 v34, s40, v10
	v_mul_f32_e32 v35, s41, v10
	v_mul_f32_e32 v36, s42, v10
	v_mul_f32_e32 v37, s43, v10
	v_mul_f32_e32 v38, s44, v10
	v_mul_f32_e32 v39, s45, v10
	v_lshlrev_b32_e32 v112, 16, v72
	v_and_b32_e32 v113, 0xffff0000, v72
	v_lshlrev_b32_e32 v114, 16, v73
	v_and_b32_e32 v115, 0xffff0000, v73
	v_lshlrev_b32_e32 v116, 16, v74
	v_and_b32_e32 v117, 0xffff0000, v74
	v_lshlrev_b32_e32 v118, 16, v75
	v_and_b32_e32 v119, 0xffff0000, v75
	v_mul_f32_e32 v140, v112, v112
	v_mul_f32_e32 v141, v113, v113
	v_fmac_f32_e32 v140, v114, v114
	v_fmac_f32_e32 v141, v115, v115
	v_fmac_f32_e32 v140, v116, v116
	v_fmac_f32_e32 v141, v117, v117
	v_fmac_f32_e32 v140, v118, v118
	v_fmac_f32_e32 v141, v119, v119
	v_add_f32_e32 v140, v140, v141
	s_nop 1
	v_add_f32_dpp v140, v140, v140 quad_perm:[1,0,3,2] row_mask:0xf bank_mask:0xf bound_ctrl:1
	s_nop 1
	v_add_f32_dpp v140, v140, v140 quad_perm:[2,3,0,1] row_mask:0xf bank_mask:0xf bound_ctrl:1
	s_nop 1
	v_add_f32_dpp v140, v140, v140 row_half_mirror row_mask:0xf bank_mask:0xf bound_ctrl:1
	v_fma_f32 v141, v140, s10, v15
	v_rsq_f32_e32 v141, v141
	s_nop 0
	v_mul_f32_e32 v112, v112, v141
	v_mul_f32_e32 v113, v113, v141
	v_mul_f32_e32 v114, v114, v141
	v_mul_f32_e32 v115, v115, v141
	v_mul_f32_e32 v116, v116, v141
	v_mul_f32_e32 v117, v117, v141
	v_mul_f32_e32 v118, v118, v141
	v_mul_f32_e32 v119, v119, v141
	v_mul_f32_e32 v112, v112, v16
	v_mul_f32_e32 v113, v113, v17
	v_mul_f32_e32 v114, v114, v18
	v_mul_f32_e32 v115, v115, v19
	v_mul_f32_e32 v116, v116, v20
	v_mul_f32_e32 v117, v117, v21
	v_mul_f32_e32 v118, v118, v22
	v_mul_f32_e32 v119, v119, v23
	v_mov_b32_dpp v120, v112 quad_perm:[1,0,3,2] row_mask:0xf bank_mask:0xf
	v_mov_b32_dpp v121, v113 quad_perm:[1,0,3,2] row_mask:0xf bank_mask:0xf
	v_mov_b32_dpp v122, v114 quad_perm:[1,0,3,2] row_mask:0xf bank_mask:0xf
	v_mov_b32_dpp v123, v115 quad_perm:[1,0,3,2] row_mask:0xf bank_mask:0xf
	v_mov_b32_dpp v124, v116 quad_perm:[1,0,3,2] row_mask:0xf bank_mask:0xf
	v_mov_b32_dpp v125, v117 quad_perm:[1,0,3,2] row_mask:0xf bank_mask:0xf
	v_mov_b32_dpp v126, v118 quad_perm:[1,0,3,2] row_mask:0xf bank_mask:0xf
	v_mov_b32_dpp v127, v119 quad_perm:[1,0,3,2] row_mask:0xf bank_mask:0xf
	v_mul_f32_e32 v128, s28, v112
	v_mul_f32_e32 v129, s29, v113
	v_mul_f32_e32 v130, s30, v114
	v_mul_f32_e32 v131, s31, v115
	v_mul_f32_e32 v132, s34, v116
	v_mul_f32_e32 v133, s35, v117
	v_mul_f32_e32 v134, s36, v118
	v_mul_f32_e32 v135, s37, v119
	v_fmac_f32_e32 v128, v32, v120
	v_fmac_f32_e32 v129, v33, v121
	v_fmac_f32_e32 v130, v34, v122
	v_fmac_f32_e32 v131, v35, v123
	v_fmac_f32_e32 v132, v36, v124
	v_fmac_f32_e32 v133, v37, v125
	v_fmac_f32_e32 v134, v38, v126
	v_fmac_f32_e32 v135, v39, v127
	v_cndmask_b32_e32 v112, v112, v128, vcc
	v_cndmask_b32_e32 v113, v113, v129, vcc
	v_cndmask_b32_e32 v114, v114, v130, vcc
	v_cndmask_b32_e32 v115, v115, v131, vcc
	v_cndmask_b32_e32 v116, v116, v132, vcc
	v_cndmask_b32_e32 v117, v117, v133, vcc
	v_cndmask_b32_e32 v118, v118, v134, vcc
	v_cndmask_b32_e32 v119, v119, v135, vcc
	v_mul_f32_e32 v112, 0x3e38aa3b, v112
	v_mul_f32_e32 v113, 0x3e38aa3b, v113
	v_mul_f32_e32 v114, 0x3e38aa3b, v114
	v_mul_f32_e32 v115, 0x3e38aa3b, v115
	v_mul_f32_e32 v116, 0x3e38aa3b, v116
	v_mul_f32_e32 v117, 0x3e38aa3b, v117
	v_mul_f32_e32 v118, 0x3e38aa3b, v118
	v_mul_f32_e32 v119, 0x3e38aa3b, v119
	v_cvt_pk_bf16_f32 v136, v112, v113
	v_cvt_pk_bf16_f32 v137, v114, v115
	v_cvt_pk_bf16_f32 v138, v116, v117
	v_cvt_pk_bf16_f32 v139, v118, v119
	global_store_dwordx4 v7, v[136:139], s[6:7]
	s_nop 1
	v_lshlrev_b32_e32 v112, 16, v76
	v_and_b32_e32 v113, 0xffff0000, v76
	v_lshlrev_b32_e32 v114, 16, v77
	v_and_b32_e32 v115, 0xffff0000, v77
	v_lshlrev_b32_e32 v116, 16, v78
	v_and_b32_e32 v117, 0xffff0000, v78
	v_lshlrev_b32_e32 v118, 16, v79
	v_and_b32_e32 v119, 0xffff0000, v79
	v_mul_f32_e32 v140, v112, v112
	v_mul_f32_e32 v141, v113, v113
	v_fmac_f32_e32 v140, v114, v114
	v_fmac_f32_e32 v141, v115, v115
	v_fmac_f32_e32 v140, v116, v116
	v_fmac_f32_e32 v141, v117, v117
	v_fmac_f32_e32 v140, v118, v118
	v_fmac_f32_e32 v141, v119, v119
	v_add_f32_e32 v140, v140, v141
	s_nop 1
	v_add_f32_dpp v140, v140, v140 quad_perm:[1,0,3,2] row_mask:0xf bank_mask:0xf bound_ctrl:1
	s_nop 1
	v_add_f32_dpp v140, v140, v140 quad_perm:[2,3,0,1] row_mask:0xf bank_mask:0xf bound_ctrl:1
	s_nop 1
	v_add_f32_dpp v140, v140, v140 row_half_mirror row_mask:0xf bank_mask:0xf bound_ctrl:1
	v_fma_f32 v141, v140, s10, v15
	v_rsq_f32_e32 v141, v141
	s_nop 0
	v_mul_f32_e32 v112, v112, v141
	v_mul_f32_e32 v113, v113, v141
	v_mul_f32_e32 v114, v114, v141
	v_mul_f32_e32 v115, v115, v141
	v_mul_f32_e32 v116, v116, v141
	v_mul_f32_e32 v117, v117, v141
	v_mul_f32_e32 v118, v118, v141
	v_mul_f32_e32 v119, v119, v141
	v_mul_f32_e32 v112, v112, v24
	v_mul_f32_e32 v113, v113, v25
	v_mul_f32_e32 v114, v114, v26
	v_mul_f32_e32 v115, v115, v27
	v_mul_f32_e32 v116, v116, v28
	v_mul_f32_e32 v117, v117, v29
	v_mul_f32_e32 v118, v118, v30
	v_mul_f32_e32 v119, v119, v31
	v_mov_b32_dpp v120, v112 quad_perm:[1,0,3,2] row_mask:0xf bank_mask:0xf
	v_mov_b32_dpp v121, v113 quad_perm:[1,0,3,2] row_mask:0xf bank_mask:0xf
	v_mov_b32_dpp v122, v114 quad_perm:[1,0,3,2] row_mask:0xf bank_mask:0xf
	v_mov_b32_dpp v123, v115 quad_perm:[1,0,3,2] row_mask:0xf bank_mask:0xf
	v_mov_b32_dpp v124, v116 quad_perm:[1,0,3,2] row_mask:0xf bank_mask:0xf
	v_mov_b32_dpp v125, v117 quad_perm:[1,0,3,2] row_mask:0xf bank_mask:0xf
	v_mov_b32_dpp v126, v118 quad_perm:[1,0,3,2] row_mask:0xf bank_mask:0xf
	v_mov_b32_dpp v127, v119 quad_perm:[1,0,3,2] row_mask:0xf bank_mask:0xf
	v_mul_f32_e32 v128, s28, v112
	v_mul_f32_e32 v129, s29, v113
	v_mul_f32_e32 v130, s30, v114
	v_mul_f32_e32 v131, s31, v115
	v_mul_f32_e32 v132, s34, v116
	v_mul_f32_e32 v133, s35, v117
	v_mul_f32_e32 v134, s36, v118
	v_mul_f32_e32 v135, s37, v119
	v_fmac_f32_e32 v128, v32, v120
	v_fmac_f32_e32 v129, v33, v121
	v_fmac_f32_e32 v130, v34, v122
	v_fmac_f32_e32 v131, v35, v123
	v_fmac_f32_e32 v132, v36, v124
	v_fmac_f32_e32 v133, v37, v125
	v_fmac_f32_e32 v134, v38, v126
	v_fmac_f32_e32 v135, v39, v127
	v_cndmask_b32_e32 v112, v112, v128, vcc
	v_cndmask_b32_e32 v113, v113, v129, vcc
	v_cndmask_b32_e32 v114, v114, v130, vcc
	v_cndmask_b32_e32 v115, v115, v131, vcc
	v_cndmask_b32_e32 v116, v116, v132, vcc
	v_cndmask_b32_e32 v117, v117, v133, vcc
	v_cndmask_b32_e32 v118, v118, v134, vcc
	v_cndmask_b32_e32 v119, v119, v135, vcc
	v_cvt_pk_bf16_f32 v136, v112, v113
	v_cvt_pk_bf16_f32 v137, v114, v115
	v_cvt_pk_bf16_f32 v138, v116, v117
	v_cvt_pk_bf16_f32 v139, v118, v119
	v_cndmask_b32_e64 v136, v136, v76, s[18:19]
	v_cndmask_b32_e64 v137, v137, v77, s[18:19]
	v_cndmask_b32_e64 v138, v138, v78, s[18:19]
	v_cndmask_b32_e64 v139, v139, v79, s[18:19]
	global_store_dwordx4 v8, v[136:139], s[12:13]
	s_add_u32 s6, s6, 0x200000
	s_addc_u32 s7, s7, 0
	s_add_u32 s12, s12, 0x80000
	s_addc_u32 s13, s13, 0
	s_waitcnt vmcnt(14)
	v_readlane_b32 s28, v11, 32
	v_readlane_b32 s38, v12, 32
	v_readlane_b32 s29, v11, 33
	v_readlane_b32 s39, v12, 33
	v_readlane_b32 s30, v11, 34
	v_readlane_b32 s40, v12, 34
	v_readlane_b32 s31, v11, 35
	v_readlane_b32 s41, v12, 35
	v_readlane_b32 s34, v11, 36
	v_readlane_b32 s42, v12, 36
	v_readlane_b32 s35, v11, 37
	v_readlane_b32 s43, v12, 37
	v_readlane_b32 s36, v11, 38
	v_readlane_b32 s44, v12, 38
	v_readlane_b32 s37, v11, 39
	v_readlane_b32 s45, v12, 39
	v_mul_f32_e32 v32, s38, v10
	v_mul_f32_e32 v33, s39, v10
	v_mul_f32_e32 v34, s40, v10
	v_mul_f32_e32 v35, s41, v10
	v_mul_f32_e32 v36, s42, v10
	v_mul_f32_e32 v37, s43, v10
	v_mul_f32_e32 v38, s44, v10
	v_mul_f32_e32 v39, s45, v10
	v_lshlrev_b32_e32 v112, 16, v80
	v_and_b32_e32 v113, 0xffff0000, v80
	v_lshlrev_b32_e32 v114, 16, v81
	v_and_b32_e32 v115, 0xffff0000, v81
	v_lshlrev_b32_e32 v116, 16, v82
	v_and_b32_e32 v117, 0xffff0000, v82
	v_lshlrev_b32_e32 v118, 16, v83
	v_and_b32_e32 v119, 0xffff0000, v83
	v_mul_f32_e32 v140, v112, v112
	v_mul_f32_e32 v141, v113, v113
	v_fmac_f32_e32 v140, v114, v114
	v_fmac_f32_e32 v141, v115, v115
	v_fmac_f32_e32 v140, v116, v116
	v_fmac_f32_e32 v141, v117, v117
	v_fmac_f32_e32 v140, v118, v118
	v_fmac_f32_e32 v141, v119, v119
	v_add_f32_e32 v140, v140, v141
	s_nop 1
	v_add_f32_dpp v140, v140, v140 quad_perm:[1,0,3,2] row_mask:0xf bank_mask:0xf bound_ctrl:1
	s_nop 1
	v_add_f32_dpp v140, v140, v140 quad_perm:[2,3,0,1] row_mask:0xf bank_mask:0xf bound_ctrl:1
	s_nop 1
	v_add_f32_dpp v140, v140, v140 row_half_mirror row_mask:0xf bank_mask:0xf bound_ctrl:1
	v_fma_f32 v141, v140, s10, v15
	v_rsq_f32_e32 v141, v141
	s_nop 0
	v_mul_f32_e32 v112, v112, v141
	v_mul_f32_e32 v113, v113, v141
	v_mul_f32_e32 v114, v114, v141
	v_mul_f32_e32 v115, v115, v141
	v_mul_f32_e32 v116, v116, v141
	v_mul_f32_e32 v117, v117, v141
	v_mul_f32_e32 v118, v118, v141
	v_mul_f32_e32 v119, v119, v141
	v_mul_f32_e32 v112, v112, v16
	v_mul_f32_e32 v113, v113, v17
	v_mul_f32_e32 v114, v114, v18
	v_mul_f32_e32 v115, v115, v19
	v_mul_f32_e32 v116, v116, v20
	v_mul_f32_e32 v117, v117, v21
	v_mul_f32_e32 v118, v118, v22
	v_mul_f32_e32 v119, v119, v23
	v_mov_b32_dpp v120, v112 quad_perm:[1,0,3,2] row_mask:0xf bank_mask:0xf
	v_mov_b32_dpp v121, v113 quad_perm:[1,0,3,2] row_mask:0xf bank_mask:0xf
	v_mov_b32_dpp v122, v114 quad_perm:[1,0,3,2] row_mask:0xf bank_mask:0xf
	v_mov_b32_dpp v123, v115 quad_perm:[1,0,3,2] row_mask:0xf bank_mask:0xf
	v_mov_b32_dpp v124, v116 quad_perm:[1,0,3,2] row_mask:0xf bank_mask:0xf
	v_mov_b32_dpp v125, v117 quad_perm:[1,0,3,2] row_mask:0xf bank_mask:0xf
	v_mov_b32_dpp v126, v118 quad_perm:[1,0,3,2] row_mask:0xf bank_mask:0xf
	v_mov_b32_dpp v127, v119 quad_perm:[1,0,3,2] row_mask:0xf bank_mask:0xf
	v_mul_f32_e32 v128, s28, v112
	v_mul_f32_e32 v129, s29, v113
	v_mul_f32_e32 v130, s30, v114
	v_mul_f32_e32 v131, s31, v115
	v_mul_f32_e32 v132, s34, v116
	v_mul_f32_e32 v133, s35, v117
	v_mul_f32_e32 v134, s36, v118
	v_mul_f32_e32 v135, s37, v119
	v_fmac_f32_e32 v128, v32, v120
	v_fmac_f32_e32 v129, v33, v121
	v_fmac_f32_e32 v130, v34, v122
	v_fmac_f32_e32 v131, v35, v123
	v_fmac_f32_e32 v132, v36, v124
	v_fmac_f32_e32 v133, v37, v125
	v_fmac_f32_e32 v134, v38, v126
	v_fmac_f32_e32 v135, v39, v127
	v_cndmask_b32_e32 v112, v112, v128, vcc
	v_cndmask_b32_e32 v113, v113, v129, vcc
	v_cndmask_b32_e32 v114, v114, v130, vcc
	v_cndmask_b32_e32 v115, v115, v131, vcc
	v_cndmask_b32_e32 v116, v116, v132, vcc
	v_cndmask_b32_e32 v117, v117, v133, vcc
	v_cndmask_b32_e32 v118, v118, v134, vcc
	v_cndmask_b32_e32 v119, v119, v135, vcc
	v_mul_f32_e32 v112, 0x3e38aa3b, v112
	v_mul_f32_e32 v113, 0x3e38aa3b, v113
	v_mul_f32_e32 v114, 0x3e38aa3b, v114
	v_mul_f32_e32 v115, 0x3e38aa3b, v115
	v_mul_f32_e32 v116, 0x3e38aa3b, v116
	v_mul_f32_e32 v117, 0x3e38aa3b, v117
	v_mul_f32_e32 v118, 0x3e38aa3b, v118
	v_mul_f32_e32 v119, 0x3e38aa3b, v119
	v_cvt_pk_bf16_f32 v136, v112, v113
	v_cvt_pk_bf16_f32 v137, v114, v115
	v_cvt_pk_bf16_f32 v138, v116, v117
	v_cvt_pk_bf16_f32 v139, v118, v119
	global_store_dwordx4 v7, v[136:139], s[6:7]
	s_nop 1
	v_lshlrev_b32_e32 v112, 16, v84
	v_and_b32_e32 v113, 0xffff0000, v84
	v_lshlrev_b32_e32 v114, 16, v85
	v_and_b32_e32 v115, 0xffff0000, v85
	v_lshlrev_b32_e32 v116, 16, v86
	v_and_b32_e32 v117, 0xffff0000, v86
	v_lshlrev_b32_e32 v118, 16, v87
	v_and_b32_e32 v119, 0xffff0000, v87
	v_mul_f32_e32 v140, v112, v112
	v_mul_f32_e32 v141, v113, v113
	v_fmac_f32_e32 v140, v114, v114
	v_fmac_f32_e32 v141, v115, v115
	v_fmac_f32_e32 v140, v116, v116
	v_fmac_f32_e32 v141, v117, v117
	v_fmac_f32_e32 v140, v118, v118
	v_fmac_f32_e32 v141, v119, v119
	v_add_f32_e32 v140, v140, v141
	s_nop 1
	v_add_f32_dpp v140, v140, v140 quad_perm:[1,0,3,2] row_mask:0xf bank_mask:0xf bound_ctrl:1
	s_nop 1
	v_add_f32_dpp v140, v140, v140 quad_perm:[2,3,0,1] row_mask:0xf bank_mask:0xf bound_ctrl:1
	s_nop 1
	v_add_f32_dpp v140, v140, v140 row_half_mirror row_mask:0xf bank_mask:0xf bound_ctrl:1
	v_fma_f32 v141, v140, s10, v15
	v_rsq_f32_e32 v141, v141
	s_nop 0
	v_mul_f32_e32 v112, v112, v141
	v_mul_f32_e32 v113, v113, v141
	v_mul_f32_e32 v114, v114, v141
	v_mul_f32_e32 v115, v115, v141
	v_mul_f32_e32 v116, v116, v141
	v_mul_f32_e32 v117, v117, v141
	v_mul_f32_e32 v118, v118, v141
	v_mul_f32_e32 v119, v119, v141
	v_mul_f32_e32 v112, v112, v24
	v_mul_f32_e32 v113, v113, v25
	v_mul_f32_e32 v114, v114, v26
	v_mul_f32_e32 v115, v115, v27
	v_mul_f32_e32 v116, v116, v28
	v_mul_f32_e32 v117, v117, v29
	v_mul_f32_e32 v118, v118, v30
	v_mul_f32_e32 v119, v119, v31
	v_mov_b32_dpp v120, v112 quad_perm:[1,0,3,2] row_mask:0xf bank_mask:0xf
	v_mov_b32_dpp v121, v113 quad_perm:[1,0,3,2] row_mask:0xf bank_mask:0xf
	v_mov_b32_dpp v122, v114 quad_perm:[1,0,3,2] row_mask:0xf bank_mask:0xf
	v_mov_b32_dpp v123, v115 quad_perm:[1,0,3,2] row_mask:0xf bank_mask:0xf
	v_mov_b32_dpp v124, v116 quad_perm:[1,0,3,2] row_mask:0xf bank_mask:0xf
	v_mov_b32_dpp v125, v117 quad_perm:[1,0,3,2] row_mask:0xf bank_mask:0xf
	v_mov_b32_dpp v126, v118 quad_perm:[1,0,3,2] row_mask:0xf bank_mask:0xf
	v_mov_b32_dpp v127, v119 quad_perm:[1,0,3,2] row_mask:0xf bank_mask:0xf
	v_mul_f32_e32 v128, s28, v112
	v_mul_f32_e32 v129, s29, v113
	v_mul_f32_e32 v130, s30, v114
	v_mul_f32_e32 v131, s31, v115
	v_mul_f32_e32 v132, s34, v116
	v_mul_f32_e32 v133, s35, v117
	v_mul_f32_e32 v134, s36, v118
	v_mul_f32_e32 v135, s37, v119
	v_fmac_f32_e32 v128, v32, v120
	v_fmac_f32_e32 v129, v33, v121
	v_fmac_f32_e32 v130, v34, v122
	v_fmac_f32_e32 v131, v35, v123
	v_fmac_f32_e32 v132, v36, v124
	v_fmac_f32_e32 v133, v37, v125
	v_fmac_f32_e32 v134, v38, v126
	v_fmac_f32_e32 v135, v39, v127
	v_cndmask_b32_e32 v112, v112, v128, vcc
	v_cndmask_b32_e32 v113, v113, v129, vcc
	v_cndmask_b32_e32 v114, v114, v130, vcc
	v_cndmask_b32_e32 v115, v115, v131, vcc
	v_cndmask_b32_e32 v116, v116, v132, vcc
	v_cndmask_b32_e32 v117, v117, v133, vcc
	v_cndmask_b32_e32 v118, v118, v134, vcc
	v_cndmask_b32_e32 v119, v119, v135, vcc
	v_cvt_pk_bf16_f32 v136, v112, v113
	v_cvt_pk_bf16_f32 v137, v114, v115
	v_cvt_pk_bf16_f32 v138, v116, v117
	v_cvt_pk_bf16_f32 v139, v118, v119
	v_cndmask_b32_e64 v136, v136, v84, s[18:19]
	v_cndmask_b32_e64 v137, v137, v85, s[18:19]
	v_cndmask_b32_e64 v138, v138, v86, s[18:19]
	v_cndmask_b32_e64 v139, v139, v87, s[18:19]
	global_store_dwordx4 v8, v[136:139], s[12:13]
	s_add_u32 s6, s6, 0x200000
	s_addc_u32 s7, s7, 0
	s_add_u32 s12, s12, 0x80000
	s_addc_u32 s13, s13, 0
	s_waitcnt vmcnt(14)
	v_readlane_b32 s28, v11, 40
	v_readlane_b32 s38, v12, 40
	v_readlane_b32 s29, v11, 41
	v_readlane_b32 s39, v12, 41
	v_readlane_b32 s30, v11, 42
	v_readlane_b32 s40, v12, 42
	v_readlane_b32 s31, v11, 43
	v_readlane_b32 s41, v12, 43
	v_readlane_b32 s34, v11, 44
	v_readlane_b32 s42, v12, 44
	v_readlane_b32 s35, v11, 45
	v_readlane_b32 s43, v12, 45
	v_readlane_b32 s36, v11, 46
	v_readlane_b32 s44, v12, 46
	v_readlane_b32 s37, v11, 47
	v_readlane_b32 s45, v12, 47
	v_mul_f32_e32 v32, s38, v10
	v_mul_f32_e32 v33, s39, v10
	v_mul_f32_e32 v34, s40, v10
	v_mul_f32_e32 v35, s41, v10
	v_mul_f32_e32 v36, s42, v10
	v_mul_f32_e32 v37, s43, v10
	v_mul_f32_e32 v38, s44, v10
	v_mul_f32_e32 v39, s45, v10
	v_lshlrev_b32_e32 v112, 16, v88
	v_and_b32_e32 v113, 0xffff0000, v88
	v_lshlrev_b32_e32 v114, 16, v89
	v_and_b32_e32 v115, 0xffff0000, v89
	v_lshlrev_b32_e32 v116, 16, v90
	v_and_b32_e32 v117, 0xffff0000, v90
	v_lshlrev_b32_e32 v118, 16, v91
	v_and_b32_e32 v119, 0xffff0000, v91
	v_mul_f32_e32 v140, v112, v112
	v_mul_f32_e32 v141, v113, v113
	v_fmac_f32_e32 v140, v114, v114
	v_fmac_f32_e32 v141, v115, v115
	v_fmac_f32_e32 v140, v116, v116
	v_fmac_f32_e32 v141, v117, v117
	v_fmac_f32_e32 v140, v118, v118
	v_fmac_f32_e32 v141, v119, v119
	v_add_f32_e32 v140, v140, v141
	s_nop 1
	v_add_f32_dpp v140, v140, v140 quad_perm:[1,0,3,2] row_mask:0xf bank_mask:0xf bound_ctrl:1
	s_nop 1
	v_add_f32_dpp v140, v140, v140 quad_perm:[2,3,0,1] row_mask:0xf bank_mask:0xf bound_ctrl:1
	s_nop 1
	v_add_f32_dpp v140, v140, v140 row_half_mirror row_mask:0xf bank_mask:0xf bound_ctrl:1
	v_fma_f32 v141, v140, s10, v15
	v_rsq_f32_e32 v141, v141
	s_nop 0
	v_mul_f32_e32 v112, v112, v141
	v_mul_f32_e32 v113, v113, v141
	v_mul_f32_e32 v114, v114, v141
	v_mul_f32_e32 v115, v115, v141
	v_mul_f32_e32 v116, v116, v141
	v_mul_f32_e32 v117, v117, v141
	v_mul_f32_e32 v118, v118, v141
	v_mul_f32_e32 v119, v119, v141
	v_mul_f32_e32 v112, v112, v16
	v_mul_f32_e32 v113, v113, v17
	v_mul_f32_e32 v114, v114, v18
	v_mul_f32_e32 v115, v115, v19
	v_mul_f32_e32 v116, v116, v20
	v_mul_f32_e32 v117, v117, v21
	v_mul_f32_e32 v118, v118, v22
	v_mul_f32_e32 v119, v119, v23
	v_mov_b32_dpp v120, v112 quad_perm:[1,0,3,2] row_mask:0xf bank_mask:0xf
	v_mov_b32_dpp v121, v113 quad_perm:[1,0,3,2] row_mask:0xf bank_mask:0xf
	v_mov_b32_dpp v122, v114 quad_perm:[1,0,3,2] row_mask:0xf bank_mask:0xf
	v_mov_b32_dpp v123, v115 quad_perm:[1,0,3,2] row_mask:0xf bank_mask:0xf
	v_mov_b32_dpp v124, v116 quad_perm:[1,0,3,2] row_mask:0xf bank_mask:0xf
	v_mov_b32_dpp v125, v117 quad_perm:[1,0,3,2] row_mask:0xf bank_mask:0xf
	v_mov_b32_dpp v126, v118 quad_perm:[1,0,3,2] row_mask:0xf bank_mask:0xf
	v_mov_b32_dpp v127, v119 quad_perm:[1,0,3,2] row_mask:0xf bank_mask:0xf
	v_mul_f32_e32 v128, s28, v112
	v_mul_f32_e32 v129, s29, v113
	v_mul_f32_e32 v130, s30, v114
	v_mul_f32_e32 v131, s31, v115
	v_mul_f32_e32 v132, s34, v116
	v_mul_f32_e32 v133, s35, v117
	v_mul_f32_e32 v134, s36, v118
	v_mul_f32_e32 v135, s37, v119
	v_fmac_f32_e32 v128, v32, v120
	v_fmac_f32_e32 v129, v33, v121
	v_fmac_f32_e32 v130, v34, v122
	v_fmac_f32_e32 v131, v35, v123
	v_fmac_f32_e32 v132, v36, v124
	v_fmac_f32_e32 v133, v37, v125
	v_fmac_f32_e32 v134, v38, v126
	v_fmac_f32_e32 v135, v39, v127
	v_cndmask_b32_e32 v112, v112, v128, vcc
	v_cndmask_b32_e32 v113, v113, v129, vcc
	v_cndmask_b32_e32 v114, v114, v130, vcc
	v_cndmask_b32_e32 v115, v115, v131, vcc
	v_cndmask_b32_e32 v116, v116, v132, vcc
	v_cndmask_b32_e32 v117, v117, v133, vcc
	v_cndmask_b32_e32 v118, v118, v134, vcc
	v_cndmask_b32_e32 v119, v119, v135, vcc
	v_mul_f32_e32 v112, 0x3e38aa3b, v112
	v_mul_f32_e32 v113, 0x3e38aa3b, v113
	v_mul_f32_e32 v114, 0x3e38aa3b, v114
	v_mul_f32_e32 v115, 0x3e38aa3b, v115
	v_mul_f32_e32 v116, 0x3e38aa3b, v116
	v_mul_f32_e32 v117, 0x3e38aa3b, v117
	v_mul_f32_e32 v118, 0x3e38aa3b, v118
	v_mul_f32_e32 v119, 0x3e38aa3b, v119
	v_cvt_pk_bf16_f32 v136, v112, v113
	v_cvt_pk_bf16_f32 v137, v114, v115
	v_cvt_pk_bf16_f32 v138, v116, v117
	v_cvt_pk_bf16_f32 v139, v118, v119
	global_store_dwordx4 v7, v[136:139], s[6:7]
	s_nop 1
	v_lshlrev_b32_e32 v112, 16, v92
	v_and_b32_e32 v113, 0xffff0000, v92
	v_lshlrev_b32_e32 v114, 16, v93
	v_and_b32_e32 v115, 0xffff0000, v93
	v_lshlrev_b32_e32 v116, 16, v94
	v_and_b32_e32 v117, 0xffff0000, v94
	v_lshlrev_b32_e32 v118, 16, v95
	v_and_b32_e32 v119, 0xffff0000, v95
	v_mul_f32_e32 v140, v112, v112
	v_mul_f32_e32 v141, v113, v113
	v_fmac_f32_e32 v140, v114, v114
	v_fmac_f32_e32 v141, v115, v115
	v_fmac_f32_e32 v140, v116, v116
	v_fmac_f32_e32 v141, v117, v117
	v_fmac_f32_e32 v140, v118, v118
	v_fmac_f32_e32 v141, v119, v119
	v_add_f32_e32 v140, v140, v141
	s_nop 1
	v_add_f32_dpp v140, v140, v140 quad_perm:[1,0,3,2] row_mask:0xf bank_mask:0xf bound_ctrl:1
	s_nop 1
	v_add_f32_dpp v140, v140, v140 quad_perm:[2,3,0,1] row_mask:0xf bank_mask:0xf bound_ctrl:1
	s_nop 1
	v_add_f32_dpp v140, v140, v140 row_half_mirror row_mask:0xf bank_mask:0xf bound_ctrl:1
	v_fma_f32 v141, v140, s10, v15
	v_rsq_f32_e32 v141, v141
	s_nop 0
	v_mul_f32_e32 v112, v112, v141
	v_mul_f32_e32 v113, v113, v141
	v_mul_f32_e32 v114, v114, v141
	v_mul_f32_e32 v115, v115, v141
	v_mul_f32_e32 v116, v116, v141
	v_mul_f32_e32 v117, v117, v141
	v_mul_f32_e32 v118, v118, v141
	v_mul_f32_e32 v119, v119, v141
	v_mul_f32_e32 v112, v112, v24
	v_mul_f32_e32 v113, v113, v25
	v_mul_f32_e32 v114, v114, v26
	v_mul_f32_e32 v115, v115, v27
	v_mul_f32_e32 v116, v116, v28
	v_mul_f32_e32 v117, v117, v29
	v_mul_f32_e32 v118, v118, v30
	v_mul_f32_e32 v119, v119, v31
	v_mov_b32_dpp v120, v112 quad_perm:[1,0,3,2] row_mask:0xf bank_mask:0xf
	v_mov_b32_dpp v121, v113 quad_perm:[1,0,3,2] row_mask:0xf bank_mask:0xf
	v_mov_b32_dpp v122, v114 quad_perm:[1,0,3,2] row_mask:0xf bank_mask:0xf
	v_mov_b32_dpp v123, v115 quad_perm:[1,0,3,2] row_mask:0xf bank_mask:0xf
	v_mov_b32_dpp v124, v116 quad_perm:[1,0,3,2] row_mask:0xf bank_mask:0xf
	v_mov_b32_dpp v125, v117 quad_perm:[1,0,3,2] row_mask:0xf bank_mask:0xf
	v_mov_b32_dpp v126, v118 quad_perm:[1,0,3,2] row_mask:0xf bank_mask:0xf
	v_mov_b32_dpp v127, v119 quad_perm:[1,0,3,2] row_mask:0xf bank_mask:0xf
	v_mul_f32_e32 v128, s28, v112
	v_mul_f32_e32 v129, s29, v113
	v_mul_f32_e32 v130, s30, v114
	v_mul_f32_e32 v131, s31, v115
	v_mul_f32_e32 v132, s34, v116
	v_mul_f32_e32 v133, s35, v117
	v_mul_f32_e32 v134, s36, v118
	v_mul_f32_e32 v135, s37, v119
	v_fmac_f32_e32 v128, v32, v120
	v_fmac_f32_e32 v129, v33, v121
	v_fmac_f32_e32 v130, v34, v122
	v_fmac_f32_e32 v131, v35, v123
	v_fmac_f32_e32 v132, v36, v124
	v_fmac_f32_e32 v133, v37, v125
	v_fmac_f32_e32 v134, v38, v126
	v_fmac_f32_e32 v135, v39, v127
	v_cndmask_b32_e32 v112, v112, v128, vcc
	v_cndmask_b32_e32 v113, v113, v129, vcc
	v_cndmask_b32_e32 v114, v114, v130, vcc
	v_cndmask_b32_e32 v115, v115, v131, vcc
	v_cndmask_b32_e32 v116, v116, v132, vcc
	v_cndmask_b32_e32 v117, v117, v133, vcc
	v_cndmask_b32_e32 v118, v118, v134, vcc
	v_cndmask_b32_e32 v119, v119, v135, vcc
	v_cvt_pk_bf16_f32 v136, v112, v113
	v_cvt_pk_bf16_f32 v137, v114, v115
	v_cvt_pk_bf16_f32 v138, v116, v117
	v_cvt_pk_bf16_f32 v139, v118, v119
	v_cndmask_b32_e64 v136, v136, v92, s[18:19]
	v_cndmask_b32_e64 v137, v137, v93, s[18:19]
	v_cndmask_b32_e64 v138, v138, v94, s[18:19]
	v_cndmask_b32_e64 v139, v139, v95, s[18:19]
	global_store_dwordx4 v8, v[136:139], s[12:13]
	s_add_u32 s6, s6, 0x200000
	s_addc_u32 s7, s7, 0
	s_add_u32 s12, s12, 0x80000
	s_addc_u32 s13, s13, 0
	s_waitcnt vmcnt(14)
	v_readlane_b32 s28, v11, 48
	v_readlane_b32 s38, v12, 48
	v_readlane_b32 s29, v11, 49
	v_readlane_b32 s39, v12, 49
	v_readlane_b32 s30, v11, 50
	v_readlane_b32 s40, v12, 50
	v_readlane_b32 s31, v11, 51
	v_readlane_b32 s41, v12, 51
	v_readlane_b32 s34, v11, 52
	v_readlane_b32 s42, v12, 52
	v_readlane_b32 s35, v11, 53
	v_readlane_b32 s43, v12, 53
	v_readlane_b32 s36, v11, 54
	v_readlane_b32 s44, v12, 54
	v_readlane_b32 s37, v11, 55
	v_readlane_b32 s45, v12, 55
	v_mul_f32_e32 v32, s38, v10
	v_mul_f32_e32 v33, s39, v10
	v_mul_f32_e32 v34, s40, v10
	v_mul_f32_e32 v35, s41, v10
	v_mul_f32_e32 v36, s42, v10
	v_mul_f32_e32 v37, s43, v10
	v_mul_f32_e32 v38, s44, v10
	v_mul_f32_e32 v39, s45, v10
	v_lshlrev_b32_e32 v112, 16, v96
	v_and_b32_e32 v113, 0xffff0000, v96
	v_lshlrev_b32_e32 v114, 16, v97
	v_and_b32_e32 v115, 0xffff0000, v97
	v_lshlrev_b32_e32 v116, 16, v98
	v_and_b32_e32 v117, 0xffff0000, v98
	v_lshlrev_b32_e32 v118, 16, v99
	v_and_b32_e32 v119, 0xffff0000, v99
	v_mul_f32_e32 v140, v112, v112
	v_mul_f32_e32 v141, v113, v113
	v_fmac_f32_e32 v140, v114, v114
	v_fmac_f32_e32 v141, v115, v115
	v_fmac_f32_e32 v140, v116, v116
	v_fmac_f32_e32 v141, v117, v117
	v_fmac_f32_e32 v140, v118, v118
	v_fmac_f32_e32 v141, v119, v119
	v_add_f32_e32 v140, v140, v141
	s_nop 1
	v_add_f32_dpp v140, v140, v140 quad_perm:[1,0,3,2] row_mask:0xf bank_mask:0xf bound_ctrl:1
	s_nop 1
	v_add_f32_dpp v140, v140, v140 quad_perm:[2,3,0,1] row_mask:0xf bank_mask:0xf bound_ctrl:1
	s_nop 1
	v_add_f32_dpp v140, v140, v140 row_half_mirror row_mask:0xf bank_mask:0xf bound_ctrl:1
	v_fma_f32 v141, v140, s10, v15
	v_rsq_f32_e32 v141, v141
	s_nop 0
	v_mul_f32_e32 v112, v112, v141
	v_mul_f32_e32 v113, v113, v141
	v_mul_f32_e32 v114, v114, v141
	v_mul_f32_e32 v115, v115, v141
	v_mul_f32_e32 v116, v116, v141
	v_mul_f32_e32 v117, v117, v141
	v_mul_f32_e32 v118, v118, v141
	v_mul_f32_e32 v119, v119, v141
	v_mul_f32_e32 v112, v112, v16
	v_mul_f32_e32 v113, v113, v17
	v_mul_f32_e32 v114, v114, v18
	v_mul_f32_e32 v115, v115, v19
	v_mul_f32_e32 v116, v116, v20
	v_mul_f32_e32 v117, v117, v21
	v_mul_f32_e32 v118, v118, v22
	v_mul_f32_e32 v119, v119, v23
	v_mov_b32_dpp v120, v112 quad_perm:[1,0,3,2] row_mask:0xf bank_mask:0xf
	v_mov_b32_dpp v121, v113 quad_perm:[1,0,3,2] row_mask:0xf bank_mask:0xf
	v_mov_b32_dpp v122, v114 quad_perm:[1,0,3,2] row_mask:0xf bank_mask:0xf
	v_mov_b32_dpp v123, v115 quad_perm:[1,0,3,2] row_mask:0xf bank_mask:0xf
	v_mov_b32_dpp v124, v116 quad_perm:[1,0,3,2] row_mask:0xf bank_mask:0xf
	v_mov_b32_dpp v125, v117 quad_perm:[1,0,3,2] row_mask:0xf bank_mask:0xf
	v_mov_b32_dpp v126, v118 quad_perm:[1,0,3,2] row_mask:0xf bank_mask:0xf
	v_mov_b32_dpp v127, v119 quad_perm:[1,0,3,2] row_mask:0xf bank_mask:0xf
	v_mul_f32_e32 v128, s28, v112
	v_mul_f32_e32 v129, s29, v113
	v_mul_f32_e32 v130, s30, v114
	v_mul_f32_e32 v131, s31, v115
	v_mul_f32_e32 v132, s34, v116
	v_mul_f32_e32 v133, s35, v117
	v_mul_f32_e32 v134, s36, v118
	v_mul_f32_e32 v135, s37, v119
	v_fmac_f32_e32 v128, v32, v120
	v_fmac_f32_e32 v129, v33, v121
	v_fmac_f32_e32 v130, v34, v122
	v_fmac_f32_e32 v131, v35, v123
	v_fmac_f32_e32 v132, v36, v124
	v_fmac_f32_e32 v133, v37, v125
	v_fmac_f32_e32 v134, v38, v126
	v_fmac_f32_e32 v135, v39, v127
	v_cndmask_b32_e32 v112, v112, v128, vcc
	v_cndmask_b32_e32 v113, v113, v129, vcc
	v_cndmask_b32_e32 v114, v114, v130, vcc
	v_cndmask_b32_e32 v115, v115, v131, vcc
	v_cndmask_b32_e32 v116, v116, v132, vcc
	v_cndmask_b32_e32 v117, v117, v133, vcc
	v_cndmask_b32_e32 v118, v118, v134, vcc
	v_cndmask_b32_e32 v119, v119, v135, vcc
	v_mul_f32_e32 v112, 0x3e38aa3b, v112
	v_mul_f32_e32 v113, 0x3e38aa3b, v113
	v_mul_f32_e32 v114, 0x3e38aa3b, v114
	v_mul_f32_e32 v115, 0x3e38aa3b, v115
	v_mul_f32_e32 v116, 0x3e38aa3b, v116
	v_mul_f32_e32 v117, 0x3e38aa3b, v117
	v_mul_f32_e32 v118, 0x3e38aa3b, v118
	v_mul_f32_e32 v119, 0x3e38aa3b, v119
	v_cvt_pk_bf16_f32 v136, v112, v113
	v_cvt_pk_bf16_f32 v137, v114, v115
	v_cvt_pk_bf16_f32 v138, v116, v117
	v_cvt_pk_bf16_f32 v139, v118, v119
	global_store_dwordx4 v7, v[136:139], s[6:7]
	s_nop 1
	v_lshlrev_b32_e32 v112, 16, v100
	v_and_b32_e32 v113, 0xffff0000, v100
	v_lshlrev_b32_e32 v114, 16, v101
	v_and_b32_e32 v115, 0xffff0000, v101
	v_lshlrev_b32_e32 v116, 16, v102
	v_and_b32_e32 v117, 0xffff0000, v102
	v_lshlrev_b32_e32 v118, 16, v103
	v_and_b32_e32 v119, 0xffff0000, v103
	v_mul_f32_e32 v140, v112, v112
	v_mul_f32_e32 v141, v113, v113
	v_fmac_f32_e32 v140, v114, v114
	v_fmac_f32_e32 v141, v115, v115
	v_fmac_f32_e32 v140, v116, v116
	v_fmac_f32_e32 v141, v117, v117
	v_fmac_f32_e32 v140, v118, v118
	v_fmac_f32_e32 v141, v119, v119
	v_add_f32_e32 v140, v140, v141
	s_nop 1
	v_add_f32_dpp v140, v140, v140 quad_perm:[1,0,3,2] row_mask:0xf bank_mask:0xf bound_ctrl:1
	s_nop 1
	v_add_f32_dpp v140, v140, v140 quad_perm:[2,3,0,1] row_mask:0xf bank_mask:0xf bound_ctrl:1
	s_nop 1
	v_add_f32_dpp v140, v140, v140 row_half_mirror row_mask:0xf bank_mask:0xf bound_ctrl:1
	v_fma_f32 v141, v140, s10, v15
	v_rsq_f32_e32 v141, v141
	s_nop 0
	v_mul_f32_e32 v112, v112, v141
	v_mul_f32_e32 v113, v113, v141
	v_mul_f32_e32 v114, v114, v141
	v_mul_f32_e32 v115, v115, v141
	v_mul_f32_e32 v116, v116, v141
	v_mul_f32_e32 v117, v117, v141
	v_mul_f32_e32 v118, v118, v141
	v_mul_f32_e32 v119, v119, v141
	v_mul_f32_e32 v112, v112, v24
	v_mul_f32_e32 v113, v113, v25
	v_mul_f32_e32 v114, v114, v26
	v_mul_f32_e32 v115, v115, v27
	v_mul_f32_e32 v116, v116, v28
	v_mul_f32_e32 v117, v117, v29
	v_mul_f32_e32 v118, v118, v30
	v_mul_f32_e32 v119, v119, v31
	v_mov_b32_dpp v120, v112 quad_perm:[1,0,3,2] row_mask:0xf bank_mask:0xf
	v_mov_b32_dpp v121, v113 quad_perm:[1,0,3,2] row_mask:0xf bank_mask:0xf
	v_mov_b32_dpp v122, v114 quad_perm:[1,0,3,2] row_mask:0xf bank_mask:0xf
	v_mov_b32_dpp v123, v115 quad_perm:[1,0,3,2] row_mask:0xf bank_mask:0xf
	v_mov_b32_dpp v124, v116 quad_perm:[1,0,3,2] row_mask:0xf bank_mask:0xf
	v_mov_b32_dpp v125, v117 quad_perm:[1,0,3,2] row_mask:0xf bank_mask:0xf
	v_mov_b32_dpp v126, v118 quad_perm:[1,0,3,2] row_mask:0xf bank_mask:0xf
	v_mov_b32_dpp v127, v119 quad_perm:[1,0,3,2] row_mask:0xf bank_mask:0xf
	v_mul_f32_e32 v128, s28, v112
	v_mul_f32_e32 v129, s29, v113
	v_mul_f32_e32 v130, s30, v114
	v_mul_f32_e32 v131, s31, v115
	v_mul_f32_e32 v132, s34, v116
	v_mul_f32_e32 v133, s35, v117
	v_mul_f32_e32 v134, s36, v118
	v_mul_f32_e32 v135, s37, v119
	v_fmac_f32_e32 v128, v32, v120
	v_fmac_f32_e32 v129, v33, v121
	v_fmac_f32_e32 v130, v34, v122
	v_fmac_f32_e32 v131, v35, v123
	v_fmac_f32_e32 v132, v36, v124
	v_fmac_f32_e32 v133, v37, v125
	v_fmac_f32_e32 v134, v38, v126
	v_fmac_f32_e32 v135, v39, v127
	v_cndmask_b32_e32 v112, v112, v128, vcc
	v_cndmask_b32_e32 v113, v113, v129, vcc
	v_cndmask_b32_e32 v114, v114, v130, vcc
	v_cndmask_b32_e32 v115, v115, v131, vcc
	v_cndmask_b32_e32 v116, v116, v132, vcc
	v_cndmask_b32_e32 v117, v117, v133, vcc
	v_cndmask_b32_e32 v118, v118, v134, vcc
	v_cndmask_b32_e32 v119, v119, v135, vcc
	v_cvt_pk_bf16_f32 v136, v112, v113
	v_cvt_pk_bf16_f32 v137, v114, v115
	v_cvt_pk_bf16_f32 v138, v116, v117
	v_cvt_pk_bf16_f32 v139, v118, v119
	v_cndmask_b32_e64 v136, v136, v100, s[18:19]
	v_cndmask_b32_e64 v137, v137, v101, s[18:19]
	v_cndmask_b32_e64 v138, v138, v102, s[18:19]
	v_cndmask_b32_e64 v139, v139, v103, s[18:19]
	global_store_dwordx4 v8, v[136:139], s[12:13]
	s_add_u32 s6, s6, 0x200000
	s_addc_u32 s7, s7, 0
	s_add_u32 s12, s12, 0x80000
	s_addc_u32 s13, s13, 0
	s_waitcnt vmcnt(14)
	v_readlane_b32 s28, v11, 56
	v_readlane_b32 s38, v12, 56
	v_readlane_b32 s29, v11, 57
	v_readlane_b32 s39, v12, 57
	v_readlane_b32 s30, v11, 58
	v_readlane_b32 s40, v12, 58
	v_readlane_b32 s31, v11, 59
	v_readlane_b32 s41, v12, 59
	v_readlane_b32 s34, v11, 60
	v_readlane_b32 s42, v12, 60
	v_readlane_b32 s35, v11, 61
	v_readlane_b32 s43, v12, 61
	v_readlane_b32 s36, v11, 62
	v_readlane_b32 s44, v12, 62
	v_readlane_b32 s37, v11, 63
	v_readlane_b32 s45, v12, 63
	v_mul_f32_e32 v32, s38, v10
	v_mul_f32_e32 v33, s39, v10
	v_mul_f32_e32 v34, s40, v10
	v_mul_f32_e32 v35, s41, v10
	v_mul_f32_e32 v36, s42, v10
	v_mul_f32_e32 v37, s43, v10
	v_mul_f32_e32 v38, s44, v10
	v_mul_f32_e32 v39, s45, v10
	v_lshlrev_b32_e32 v112, 16, v104
	v_and_b32_e32 v113, 0xffff0000, v104
	v_lshlrev_b32_e32 v114, 16, v105
	v_and_b32_e32 v115, 0xffff0000, v105
	v_lshlrev_b32_e32 v116, 16, v106
	v_and_b32_e32 v117, 0xffff0000, v106
	v_lshlrev_b32_e32 v118, 16, v107
	v_and_b32_e32 v119, 0xffff0000, v107
	v_mul_f32_e32 v140, v112, v112
	v_mul_f32_e32 v141, v113, v113
	v_fmac_f32_e32 v140, v114, v114
	v_fmac_f32_e32 v141, v115, v115
	v_fmac_f32_e32 v140, v116, v116
	v_fmac_f32_e32 v141, v117, v117
	v_fmac_f32_e32 v140, v118, v118
	v_fmac_f32_e32 v141, v119, v119
	v_add_f32_e32 v140, v140, v141
	s_nop 1
	v_add_f32_dpp v140, v140, v140 quad_perm:[1,0,3,2] row_mask:0xf bank_mask:0xf bound_ctrl:1
	s_nop 1
	v_add_f32_dpp v140, v140, v140 quad_perm:[2,3,0,1] row_mask:0xf bank_mask:0xf bound_ctrl:1
	s_nop 1
	v_add_f32_dpp v140, v140, v140 row_half_mirror row_mask:0xf bank_mask:0xf bound_ctrl:1
	v_fma_f32 v141, v140, s10, v15
	v_rsq_f32_e32 v141, v141
	s_nop 0
	v_mul_f32_e32 v112, v112, v141
	v_mul_f32_e32 v113, v113, v141
	v_mul_f32_e32 v114, v114, v141
	v_mul_f32_e32 v115, v115, v141
	v_mul_f32_e32 v116, v116, v141
	v_mul_f32_e32 v117, v117, v141
	v_mul_f32_e32 v118, v118, v141
	v_mul_f32_e32 v119, v119, v141
	v_mul_f32_e32 v112, v112, v16
	v_mul_f32_e32 v113, v113, v17
	v_mul_f32_e32 v114, v114, v18
	v_mul_f32_e32 v115, v115, v19
	v_mul_f32_e32 v116, v116, v20
	v_mul_f32_e32 v117, v117, v21
	v_mul_f32_e32 v118, v118, v22
	v_mul_f32_e32 v119, v119, v23
	v_mov_b32_dpp v120, v112 quad_perm:[1,0,3,2] row_mask:0xf bank_mask:0xf
	v_mov_b32_dpp v121, v113 quad_perm:[1,0,3,2] row_mask:0xf bank_mask:0xf
	v_mov_b32_dpp v122, v114 quad_perm:[1,0,3,2] row_mask:0xf bank_mask:0xf
	v_mov_b32_dpp v123, v115 quad_perm:[1,0,3,2] row_mask:0xf bank_mask:0xf
	v_mov_b32_dpp v124, v116 quad_perm:[1,0,3,2] row_mask:0xf bank_mask:0xf
	v_mov_b32_dpp v125, v117 quad_perm:[1,0,3,2] row_mask:0xf bank_mask:0xf
	v_mov_b32_dpp v126, v118 quad_perm:[1,0,3,2] row_mask:0xf bank_mask:0xf
	v_mov_b32_dpp v127, v119 quad_perm:[1,0,3,2] row_mask:0xf bank_mask:0xf
	v_mul_f32_e32 v128, s28, v112
	v_mul_f32_e32 v129, s29, v113
	v_mul_f32_e32 v130, s30, v114
	v_mul_f32_e32 v131, s31, v115
	v_mul_f32_e32 v132, s34, v116
	v_mul_f32_e32 v133, s35, v117
	v_mul_f32_e32 v134, s36, v118
	v_mul_f32_e32 v135, s37, v119
	v_fmac_f32_e32 v128, v32, v120
	v_fmac_f32_e32 v129, v33, v121
	v_fmac_f32_e32 v130, v34, v122
	v_fmac_f32_e32 v131, v35, v123
	v_fmac_f32_e32 v132, v36, v124
	v_fmac_f32_e32 v133, v37, v125
	v_fmac_f32_e32 v134, v38, v126
	v_fmac_f32_e32 v135, v39, v127
	v_cndmask_b32_e32 v112, v112, v128, vcc
	v_cndmask_b32_e32 v113, v113, v129, vcc
	v_cndmask_b32_e32 v114, v114, v130, vcc
	v_cndmask_b32_e32 v115, v115, v131, vcc
	v_cndmask_b32_e32 v116, v116, v132, vcc
	v_cndmask_b32_e32 v117, v117, v133, vcc
	v_cndmask_b32_e32 v118, v118, v134, vcc
	v_cndmask_b32_e32 v119, v119, v135, vcc
	v_mul_f32_e32 v112, 0x3e38aa3b, v112
	v_mul_f32_e32 v113, 0x3e38aa3b, v113
	v_mul_f32_e32 v114, 0x3e38aa3b, v114
	v_mul_f32_e32 v115, 0x3e38aa3b, v115
	v_mul_f32_e32 v116, 0x3e38aa3b, v116
	v_mul_f32_e32 v117, 0x3e38aa3b, v117
	v_mul_f32_e32 v118, 0x3e38aa3b, v118
	v_mul_f32_e32 v119, 0x3e38aa3b, v119
	v_cvt_pk_bf16_f32 v136, v112, v113
	v_cvt_pk_bf16_f32 v137, v114, v115
	v_cvt_pk_bf16_f32 v138, v116, v117
	v_cvt_pk_bf16_f32 v139, v118, v119
	global_store_dwordx4 v7, v[136:139], s[6:7]
	s_nop 1
	v_lshlrev_b32_e32 v112, 16, v108
	v_and_b32_e32 v113, 0xffff0000, v108
	v_lshlrev_b32_e32 v114, 16, v109
	v_and_b32_e32 v115, 0xffff0000, v109
	v_lshlrev_b32_e32 v116, 16, v110
	v_and_b32_e32 v117, 0xffff0000, v110
	v_lshlrev_b32_e32 v118, 16, v111
	v_and_b32_e32 v119, 0xffff0000, v111
	v_mul_f32_e32 v140, v112, v112
	v_mul_f32_e32 v141, v113, v113
	v_fmac_f32_e32 v140, v114, v114
	v_fmac_f32_e32 v141, v115, v115
	v_fmac_f32_e32 v140, v116, v116
	v_fmac_f32_e32 v141, v117, v117
	v_fmac_f32_e32 v140, v118, v118
	v_fmac_f32_e32 v141, v119, v119
	v_add_f32_e32 v140, v140, v141
	s_nop 1
	v_add_f32_dpp v140, v140, v140 quad_perm:[1,0,3,2] row_mask:0xf bank_mask:0xf bound_ctrl:1
	s_nop 1
	v_add_f32_dpp v140, v140, v140 quad_perm:[2,3,0,1] row_mask:0xf bank_mask:0xf bound_ctrl:1
	s_nop 1
	v_add_f32_dpp v140, v140, v140 row_half_mirror row_mask:0xf bank_mask:0xf bound_ctrl:1
	v_fma_f32 v141, v140, s10, v15
	v_rsq_f32_e32 v141, v141
	s_nop 0
	v_mul_f32_e32 v112, v112, v141
	v_mul_f32_e32 v113, v113, v141
	v_mul_f32_e32 v114, v114, v141
	v_mul_f32_e32 v115, v115, v141
	v_mul_f32_e32 v116, v116, v141
	v_mul_f32_e32 v117, v117, v141
	v_mul_f32_e32 v118, v118, v141
	v_mul_f32_e32 v119, v119, v141
	v_mul_f32_e32 v112, v112, v24
	v_mul_f32_e32 v113, v113, v25
	v_mul_f32_e32 v114, v114, v26
	v_mul_f32_e32 v115, v115, v27
	v_mul_f32_e32 v116, v116, v28
	v_mul_f32_e32 v117, v117, v29
	v_mul_f32_e32 v118, v118, v30
	v_mul_f32_e32 v119, v119, v31
	v_mov_b32_dpp v120, v112 quad_perm:[1,0,3,2] row_mask:0xf bank_mask:0xf
	v_mov_b32_dpp v121, v113 quad_perm:[1,0,3,2] row_mask:0xf bank_mask:0xf
	v_mov_b32_dpp v122, v114 quad_perm:[1,0,3,2] row_mask:0xf bank_mask:0xf
	v_mov_b32_dpp v123, v115 quad_perm:[1,0,3,2] row_mask:0xf bank_mask:0xf
	v_mov_b32_dpp v124, v116 quad_perm:[1,0,3,2] row_mask:0xf bank_mask:0xf
	v_mov_b32_dpp v125, v117 quad_perm:[1,0,3,2] row_mask:0xf bank_mask:0xf
	v_mov_b32_dpp v126, v118 quad_perm:[1,0,3,2] row_mask:0xf bank_mask:0xf
	v_mov_b32_dpp v127, v119 quad_perm:[1,0,3,2] row_mask:0xf bank_mask:0xf
	v_mul_f32_e32 v128, s28, v112
	v_mul_f32_e32 v129, s29, v113
	v_mul_f32_e32 v130, s30, v114
	v_mul_f32_e32 v131, s31, v115
	v_mul_f32_e32 v132, s34, v116
	v_mul_f32_e32 v133, s35, v117
	v_mul_f32_e32 v134, s36, v118
	v_mul_f32_e32 v135, s37, v119
	v_fmac_f32_e32 v128, v32, v120
	v_fmac_f32_e32 v129, v33, v121
	v_fmac_f32_e32 v130, v34, v122
	v_fmac_f32_e32 v131, v35, v123
	v_fmac_f32_e32 v132, v36, v124
	v_fmac_f32_e32 v133, v37, v125
	v_fmac_f32_e32 v134, v38, v126
	v_fmac_f32_e32 v135, v39, v127
	v_cndmask_b32_e32 v112, v112, v128, vcc
	v_cndmask_b32_e32 v113, v113, v129, vcc
	v_cndmask_b32_e32 v114, v114, v130, vcc
	v_cndmask_b32_e32 v115, v115, v131, vcc
	v_cndmask_b32_e32 v116, v116, v132, vcc
	v_cndmask_b32_e32 v117, v117, v133, vcc
	v_cndmask_b32_e32 v118, v118, v134, vcc
	v_cndmask_b32_e32 v119, v119, v135, vcc
	v_cvt_pk_bf16_f32 v136, v112, v113
	v_cvt_pk_bf16_f32 v137, v114, v115
	v_cvt_pk_bf16_f32 v138, v116, v117
	v_cvt_pk_bf16_f32 v139, v118, v119
	v_cndmask_b32_e64 v136, v136, v108, s[18:19]
	v_cndmask_b32_e64 v137, v137, v109, s[18:19]
	v_cndmask_b32_e64 v138, v138, v110, s[18:19]
	v_cndmask_b32_e64 v139, v139, v111, s[18:19]
	global_store_dwordx4 v8, v[136:139], s[12:13]
	s_add_u32 s6, s6, 0x200000
	s_addc_u32 s7, s7, 0
	s_add_u32 s12, s12, 0x80000
	s_addc_u32 s13, s13, 0
	s_branch .LBB0_278
	s_nop 0
	s_nop 0
	s_nop 0
	s_nop 0
	s_nop 0
	s_nop 0
	s_nop 0
	s_nop 0
.Lnsp_generic:
	v_lshlrev_b32_e32 v2, 2, v4
	global_load_dword v5, v2, s[2:3]
	global_load_dword v6, v2, s[4:5]
	global_load_dword v7, v2, s[4:5] offset:256
	global_load_dword v8, v2, s[4:5] offset:512
	v_and_b32_e32 v2, 7, v4
	v_cmp_eq_u32_e32 vcc, 0, v2
	v_mov_b32_e32 v9, 0x3e4693af
	s_add_u32 s27, s11, 0xb800000
	v_cndmask_b32_e64 v3, 0, 1.0, vcc
	v_cmp_ne_u32_e32 vcc, 1, v2
	s_addc_u32 s28, s20, 0
	s_add_u32 s29, s11, 0xc800000
	v_cndmask_b32_e32 v3, v9, v3, vcc
	v_mov_b32_e32 v9, 0x3d1a08c8
	v_cmp_ne_u32_e32 vcc, 2, v2
	s_addc_u32 s30, s20, 0
	s_add_u32 s31, s11, 0xcd00000
	v_cndmask_b32_e32 v3, v9, v3, vcc
	v_mov_b32_e32 v9, 0x3beef74e
	v_cmp_ne_u32_e32 vcc, 3, v2
	s_addc_u32 s34, s20, 0
	s_add_u32 s35, s11, 0xd200000
	v_cndmask_b32_e32 v3, v9, v3, vcc
	v_mov_b32_e32 v9, 0x3ab95d22
	v_cmp_ne_u32_e32 vcc, 4, v2
	s_addc_u32 s36, s20, 0
	s_add_u32 s37, s11, 0xdc00000
	v_cndmask_b32_e32 v3, v9, v3, vcc
	v_mov_b32_e32 v9, 0x398fc8f8
	v_cmp_ne_u32_e32 vcc, 5, v2
	v_cmp_gt_u32_e64 s[0:1], 16, v4
	s_addc_u32 s38, s20, 0
	v_cndmask_b32_e32 v3, v9, v3, vcc
	v_mov_b32_e32 v9, 0x385f10c4
	v_cmp_ne_u32_e32 vcc, 6, v2
	s_mov_b64 s[6:7], 0x1000
	s_movk_i32 s39, 0x1000
	v_cndmask_b32_e32 v3, v9, v3, vcc
	v_cmp_ne_u32_e32 vcc, 7, v2
	v_mbcnt_lo_u32_b32 v2, -1, 0
	v_mbcnt_hi_u32_b32 v2, -1, v2
	v_mov_b32_e32 v9, 0x372d07a7
	v_and_b32_e32 v10, 64, v2
	v_cndmask_b32_e32 v9, v9, v3, vcc
	v_xor_b32_e32 v3, 16, v2
	v_add_u32_e32 v11, 64, v10
	v_cmp_lt_i32_e64 s[2:3], v3, v11
	v_cmp_gt_i32_e32 vcc, 8, v4
	s_mov_b32 s10, 0x3c800000
	v_cndmask_b32_e64 v3, v2, v3, s[2:3]
	v_lshlrev_b32_e32 v10, 2, v3
	v_xor_b32_e32 v3, 32, v2
	v_cmp_lt_i32_e64 s[2:3], v3, v11
	s_mov_b32 s40, 0x800000
	s_movk_i32 s41, 0x7fff
	v_cndmask_b32_e64 v2, v2, v3, s[2:3]
	s_mov_b32 s2, 0x358637bd
	v_lshlrev_b32_e32 v11, 2, v2
	v_mov_b64_e32 v[2:3], s[2:3]
	s_mov_b32 s12, s84

.LBB0_409:
	s_or_b64 exec, exec, s[0:1]
	s_add_i32 s7, 0, 0x23fa0
	s_add_i32 s0, 0, 0x23f40
	s_mov_b32 s6, -1
	v_mov_b32_e32 v0, s7
	v_mov_b32_e32 v4, s0
	s_barrier
	ds_read_b128 v[0:3], v0
	ds_read_b64 v[4:5], v4
	v_readlane_b32 s8, v247, 12
	v_readlane_b32 s9, v247, 13
	s_mov_b32 s10, -1
	s_waitcnt lgkmcnt(1)
	v_readfirstlane_b32 s0, v0
	v_readfirstlane_b32 s1, v1
	v_readfirstlane_b32 s2, v2
	v_readfirstlane_b32 s3, v3
	s_waitcnt lgkmcnt(0)
	v_readfirstlane_b32 s4, v4
	s_and_b64 vcc, exec, s[8:9]
	v_readfirstlane_b32 s5, v5
	s_cbranch_vccnz .LBB0_412
	s_cmpk_lg_i32 s76, 0x100
	s_cbranch_scc1 .Lhgn_generic
	s_lshl_b32 s11, s84, 6
	s_add_u32 s8, s0, s11
	s_addc_u32 s9, s1, 0
	s_mul_i32 s11, s84, 0x1c00
	s_add_u32 s12, s2, s11
	s_addc_u32 s13, s3, 0
	s_add_u32 s12, s12, 0x4800c00
	s_addc_u32 s13, s13, 0
	s_lshl_b32 s11, s84, 11
	s_add_u32 s14, s2, s11
	s_addc_u32 s15, s3, 0
	s_add_u32 s14, s14, 0x2800000
	s_addc_u32 s15, s15, 0
	s_mov_b32 s6, 0x3c000000
	v_mov_b32_e32 v10, 0x358637bd
	v_mbcnt_lo_u32_b32 v0, -1, 0
	v_mbcnt_hi_u32_b32 v0, -1, v0
	v_lshlrev_b32_e32 v1, 2, v0
	v_lshlrev_b32_e32 v2, 3, v0
	v_lshrrev_b32_e32 v3, 3, v0
	v_lshlrev_b32_e32 v3, 17, v3
	v_and_b32_e32 v4, 7, v0
	v_lshl_add_u32 v3, v4, 3, v3
	v_xor_b32_e32 v4, 16, v0
	v_xor_b32_e32 v5, 32, v0
	v_lshlrev_b32_e32 v4, 2, v4
	v_lshlrev_b32_e32 v5, 2, v5
	global_load_dwordx2 v[16:17], v3, s[8:9]
	s_add_u32 s8, s8, 0x100000
	s_addc_u32 s9, s9, 0
	global_load_dwordx2 v[18:19], v3, s[8:9]
	s_add_u32 s8, s8, 0x100000
	s_addc_u32 s9, s9, 0
	global_load_dwordx2 v[20:21], v3, s[8:9]
	s_add_u32 s8, s8, 0x100000
	s_addc_u32 s9, s9, 0
	global_load_dwordx2 v[22:23], v3, s[8:9]
	s_add_u32 s8, s8, 0x100000
	s_addc_u32 s9, s9, 0
	global_load_dword v24, v1, s[12:13]
	global_load_dword v25, v1, s[12:13] offset:256
	global_load_dword v26, v1, s[12:13] offset:512
	global_load_dword v27, v1, s[12:13] offset:768
	s_add_u32 s12, s12, 0xe00000
	s_addc_u32 s13, s13, 0
	global_load_dwordx2 v[6:7], v2, s[4:5]
	global_load_dwordx2 v[28:29], v3, s[8:9]
	s_add_u32 s8, s8, 0x100000
	s_addc_u32 s9, s9, 0
	global_load_dwordx2 v[30:31], v3, s[8:9]
	s_add_u32 s8, s8, 0x100000
	s_addc_u32 s9, s9, 0
	global_load_dwordx2 v[32:33], v3, s[8:9]
	s_add_u32 s8, s8, 0x100000
	s_addc_u32 s9, s9, 0
	global_load_dwordx2 v[34:35], v3, s[8:9]
	s_add_u32 s8, s8, 0x100000
	s_addc_u32 s9, s9, 0
	global_load_dword v36, v1, s[12:13]
	global_load_dword v37, v1, s[12:13] offset:256
	global_load_dword v38, v1, s[12:13] offset:512
	global_load_dword v39, v1, s[12:13] offset:768
	s_add_u32 s12, s12, 0xe00000
	s_addc_u32 s13, s13, 0
	global_load_dwordx2 v[40:41], v3, s[8:9]
	s_add_u32 s8, s8, 0x100000
	s_addc_u32 s9, s9, 0
	global_load_dwordx2 v[42:43], v3, s[8:9]
	s_add_u32 s8, s8, 0x100000
	s_addc_u32 s9, s9, 0
	global_load_dwordx2 v[44:45], v3, s[8:9]
	s_add_u32 s8, s8, 0x100000
	s_addc_u32 s9, s9, 0
	global_load_dwordx2 v[46:47], v3, s[8:9]
	s_add_u32 s8, s8, 0x100000
	s_addc_u32 s9, s9, 0
	global_load_dword v48, v1, s[12:13]
	global_load_dword v49, v1, s[12:13] offset:256
	global_load_dword v50, v1, s[12:13] offset:512
	global_load_dword v51, v1, s[12:13] offset:768
	s_add_u32 s12, s12, 0xe00000
	s_addc_u32 s13, s13, 0
	global_load_dwordx2 v[52:53], v3, s[8:9]
	s_add_u32 s8, s8, 0x100000
	s_addc_u32 s9, s9, 0
	global_load_dwordx2 v[54:55], v3, s[8:9]
	s_add_u32 s8, s8, 0x100000
	s_addc_u32 s9, s9, 0
	global_load_dwordx2 v[56:57], v3, s[8:9]
	s_add_u32 s8, s8, 0x100000
	s_addc_u32 s9, s9, 0
	global_load_dwordx2 v[58:59], v3, s[8:9]
	s_add_u32 s8, s8, 0x100000
	s_addc_u32 s9, s9, 0
	global_load_dword v60, v1, s[12:13]
	global_load_dword v61, v1, s[12:13] offset:256
	global_load_dword v62, v1, s[12:13] offset:512
	global_load_dword v63, v1, s[12:13] offset:768
	s_add_u32 s12, s12, 0xe00000
	s_addc_u32 s13, s13, 0
	global_load_dwordx2 v[64:65], v3, s[8:9]
	s_add_u32 s8, s8, 0x100000
	s_addc_u32 s9, s9, 0
	global_load_dwordx2 v[66:67], v3, s[8:9]
	s_add_u32 s8, s8, 0x100000
	s_addc_u32 s9, s9, 0
	global_load_dwordx2 v[68:69], v3, s[8:9]
	s_add_u32 s8, s8, 0x100000
	s_addc_u32 s9, s9, 0
	global_load_dwordx2 v[70:71], v3, s[8:9]
	s_add_u32 s8, s8, 0x100000
	s_addc_u32 s9, s9, 0
	global_load_dword v72, v1, s[12:13]
	global_load_dword v73, v1, s[12:13] offset:256
	global_load_dword v74, v1, s[12:13] offset:512
	global_load_dword v75, v1, s[12:13] offset:768
	s_add_u32 s12, s12, 0xe00000
	s_addc_u32 s13, s13, 0
	global_load_dwordx2 v[76:77], v3, s[8:9]
	s_add_u32 s8, s8, 0x100000
	s_addc_u32 s9, s9, 0
	global_load_dwordx2 v[78:79], v3, s[8:9]
	s_add_u32 s8, s8, 0x100000
	s_addc_u32 s9, s9, 0
	global_load_dwordx2 v[80:81], v3, s[8:9]
	s_add_u32 s8, s8, 0x100000
	s_addc_u32 s9, s9, 0
	global_load_dwordx2 v[82:83], v3, s[8:9]
	s_add_u32 s8, s8, 0x100000
	s_addc_u32 s9, s9, 0
	global_load_dword v84, v1, s[12:13]
	global_load_dword v85, v1, s[12:13] offset:256
	global_load_dword v86, v1, s[12:13] offset:512
	global_load_dword v87, v1, s[12:13] offset:768
	s_add_u32 s12, s12, 0xe00000
	s_addc_u32 s13, s13, 0
	s_waitcnt vmcnt(41)
	v_mul_f32_e32 v112, v16, v16
	v_mul_f32_e32 v113, v18, v18
	v_mul_f32_e32 v114, v20, v20
	v_mul_f32_e32 v115, v22, v22
	v_fmac_f32_e32 v112, v17, v17
	v_fmac_f32_e32 v113, v19, v19
	v_fmac_f32_e32 v114, v21, v21
	v_fmac_f32_e32 v115, v23, v23
	v_lshlrev_b32_e32 v124, 16, v24
	v_and_b32_e32 v125, 0xffff0000, v24
	v_lshlrev_b32_e32 v126, 16, v25
	v_and_b32_e32 v127, 0xffff0000, v25
	v_lshlrev_b32_e32 v128, 16, v26
	v_and_b32_e32 v129, 0xffff0000, v26
	v_lshlrev_b32_e32 v130, 16, v27
	v_and_b32_e32 v131, 0xffff0000, v27
	v_add_f32_dpp v112, v112, v112 quad_perm:[1,0,3,2] row_mask:0xf bank_mask:0xf bound_ctrl:1
	v_add_f32_dpp v113, v113, v113 quad_perm:[1,0,3,2] row_mask:0xf bank_mask:0xf bound_ctrl:1
	v_add_f32_dpp v114, v114, v114 quad_perm:[1,0,3,2] row_mask:0xf bank_mask:0xf bound_ctrl:1
	v_add_f32_dpp v115, v115, v115 quad_perm:[1,0,3,2] row_mask:0xf bank_mask:0xf bound_ctrl:1
	v_add_f32_dpp v112, v112, v112 quad_perm:[2,3,0,1] row_mask:0xf bank_mask:0xf bound_ctrl:1
	v_add_f32_dpp v113, v113, v113 quad_perm:[2,3,0,1] row_mask:0xf bank_mask:0xf bound_ctrl:1
	v_add_f32_dpp v114, v114, v114 quad_perm:[2,3,0,1] row_mask:0xf bank_mask:0xf bound_ctrl:1
	v_add_f32_dpp v115, v115, v115 quad_perm:[2,3,0,1] row_mask:0xf bank_mask:0xf bound_ctrl:1
	v_add_f32_dpp v112, v112, v112 row_half_mirror row_mask:0xf bank_mask:0xf bound_ctrl:1
	v_add_f32_dpp v113, v113, v113 row_half_mirror row_mask:0xf bank_mask:0xf bound_ctrl:1
	v_add_f32_dpp v114, v114, v114 row_half_mirror row_mask:0xf bank_mask:0xf bound_ctrl:1
	v_add_f32_dpp v115, v115, v115 row_half_mirror row_mask:0xf bank_mask:0xf bound_ctrl:1
	v_add_f32_dpp v112, v112, v112 row_mirror row_mask:0xf bank_mask:0xf bound_ctrl:1
	v_add_f32_dpp v113, v113, v113 row_mirror row_mask:0xf bank_mask:0xf bound_ctrl:1
	v_add_f32_dpp v114, v114, v114 row_mirror row_mask:0xf bank_mask:0xf bound_ctrl:1
	v_add_f32_dpp v115, v115, v115 row_mirror row_mask:0xf bank_mask:0xf bound_ctrl:1
	ds_bpermute_b32 v116, v4, v112
	ds_bpermute_b32 v117, v4, v113
	ds_bpermute_b32 v118, v4, v114
	ds_bpermute_b32 v119, v4, v115
	v_mul_f32_e32 v132, 0xbfb8aa3b, v124
	v_mul_f32_e32 v133, 0xbfb8aa3b, v125
	v_mul_f32_e32 v134, 0xbfb8aa3b, v126
	v_mul_f32_e32 v135, 0xbfb8aa3b, v127
	v_mul_f32_e32 v136, 0xbfb8aa3b, v128
	v_mul_f32_e32 v137, 0xbfb8aa3b, v129
	v_mul_f32_e32 v138, 0xbfb8aa3b, v130
	v_mul_f32_e32 v139, 0xbfb8aa3b, v131
	s_waitcnt lgkmcnt(0)
	v_add_f32_e32 v112, v112, v116
	v_add_f32_e32 v113, v113, v117
	v_add_f32_e32 v114, v114, v118
	v_add_f32_e32 v115, v115, v119
	ds_bpermute_b32 v116, v5, v112
	ds_bpermute_b32 v117, v5, v113
	ds_bpermute_b32 v118, v5, v114
	ds_bpermute_b32 v119, v5, v115
	v_exp_f32_e32 v132, v132
	v_exp_f32_e32 v133, v133
	v_exp_f32_e32 v134, v134
	v_exp_f32_e32 v135, v135
	v_exp_f32_e32 v136, v136
	v_exp_f32_e32 v137, v137
	v_exp_f32_e32 v138, v138
	v_exp_f32_e32 v139, v139
	v_add_f32_e32 v132, 1.0, v132
	v_add_f32_e32 v133, 1.0, v133
	v_add_f32_e32 v134, 1.0, v134
	v_add_f32_e32 v135, 1.0, v135
	v_add_f32_e32 v136, 1.0, v136
	v_add_f32_e32 v137, 1.0, v137
	v_add_f32_e32 v138, 1.0, v138
	v_add_f32_e32 v139, 1.0, v139
	v_rcp_f32_e32 v132, v132
	v_rcp_f32_e32 v133, v133
	v_rcp_f32_e32 v134, v134
	v_rcp_f32_e32 v135, v135
	v_rcp_f32_e32 v136, v136
	v_rcp_f32_e32 v137, v137
	v_rcp_f32_e32 v138, v138
	v_rcp_f32_e32 v139, v139
	s_waitcnt lgkmcnt(0)
	v_add_f32_e32 v112, v112, v116
	v_add_f32_e32 v113, v113, v117
	v_add_f32_e32 v114, v114, v118
	v_add_f32_e32 v115, v115, v119
	v_mul_f32_e32 v124, v132, v124
	v_mul_f32_e32 v125, v133, v125
	v_mul_f32_e32 v126, v134, v126
	v_mul_f32_e32 v127, v135, v127
	v_mul_f32_e32 v128, v136, v128
	v_mul_f32_e32 v129, v137, v129
	v_mul_f32_e32 v130, v138, v130
	v_mul_f32_e32 v131, v139, v131
	v_fma_f32 v120, v112, s6, v10
	v_fma_f32 v121, v113, s6, v10
	v_fma_f32 v122, v114, s6, v10
	v_fma_f32 v123, v115, s6, v10
	v_rsq_f32_e32 v120, v120
	v_rsq_f32_e32 v121, v121
	v_rsq_f32_e32 v122, v122
	v_rsq_f32_e32 v123, v123
	s_waitcnt vmcnt(40)
	s_nop 0
	v_mul_f32_e32 v16, v16, v120
	v_mul_f32_e32 v17, v17, v120
	v_mul_f32_e32 v18, v18, v121
	v_mul_f32_e32 v19, v19, v121
	v_mul_f32_e32 v20, v20, v122
	v_mul_f32_e32 v21, v21, v122
	v_mul_f32_e32 v22, v22, v123
	v_mul_f32_e32 v23, v23, v123
	v_mul_f32_e32 v16, v6, v16
	v_mul_f32_e32 v17, v7, v17
	v_mul_f32_e32 v18, v6, v18
	v_mul_f32_e32 v19, v7, v19
	v_mul_f32_e32 v20, v6, v20
	v_mul_f32_e32 v21, v7, v21
	v_mul_f32_e32 v22, v6, v22
	v_mul_f32_e32 v23, v7, v23
	v_mul_f32_e32 v16, v124, v16
	v_mul_f32_e32 v17, v125, v17
	v_mul_f32_e32 v18, v126, v18
	v_mul_f32_e32 v19, v127, v19
	v_mul_f32_e32 v20, v128, v20
	v_mul_f32_e32 v21, v129, v21
	v_mul_f32_e32 v22, v130, v22
	v_mul_f32_e32 v23, v131, v23
	v_cvt_pk_bf16_f32 v140, v16, v17
	v_cvt_pk_bf16_f32 v141, v18, v19
	v_cvt_pk_bf16_f32 v142, v20, v21
	v_cvt_pk_bf16_f32 v143, v22, v23
	global_store_dword v1, v140, s[14:15]
	global_store_dword v1, v141, s[14:15] offset:256
	global_store_dword v1, v142, s[14:15] offset:512
	global_store_dword v1, v143, s[14:15] offset:768
	s_add_u32 s14, s14, 0x400000
	s_addc_u32 s15, s15, 0
	global_load_dwordx2 v[88:89], v3, s[8:9]
	s_add_u32 s8, s8, 0x100000
	s_addc_u32 s9, s9, 0
	global_load_dwordx2 v[90:91], v3, s[8:9]
	s_add_u32 s8, s8, 0x100000
	s_addc_u32 s9, s9, 0
	global_load_dwordx2 v[92:93], v3, s[8:9]
	s_add_u32 s8, s8, 0x100000
	s_addc_u32 s9, s9, 0
	global_load_dwordx2 v[94:95], v3, s[8:9]
	s_add_u32 s8, s8, 0x100000
	s_addc_u32 s9, s9, 0
	global_load_dword v96, v1, s[12:13]
	global_load_dword v97, v1, s[12:13] offset:256
	global_load_dword v98, v1, s[12:13] offset:512
	global_load_dword v99, v1, s[12:13] offset:768
	s_add_u32 s12, s12, 0xe00000
	s_addc_u32 s13, s13, 0
	s_waitcnt vmcnt(44)
	v_mul_f32_e32 v112, v28, v28
	v_mul_f32_e32 v113, v30, v30
	v_mul_f32_e32 v114, v32, v32
	v_mul_f32_e32 v115, v34, v34
	v_fmac_f32_e32 v112, v29, v29
	v_fmac_f32_e32 v113, v31, v31
	v_fmac_f32_e32 v114, v33, v33
	v_fmac_f32_e32 v115, v35, v35
	v_lshlrev_b32_e32 v124, 16, v36
	v_and_b32_e32 v125, 0xffff0000, v36
	v_lshlrev_b32_e32 v126, 16, v37
	v_and_b32_e32 v127, 0xffff0000, v37
	v_lshlrev_b32_e32 v128, 16, v38
	v_and_b32_e32 v129, 0xffff0000, v38
	v_lshlrev_b32_e32 v130, 16, v39
	v_and_b32_e32 v131, 0xffff0000, v39
	v_add_f32_dpp v112, v112, v112 quad_perm:[1,0,3,2] row_mask:0xf bank_mask:0xf bound_ctrl:1
	v_add_f32_dpp v113, v113, v113 quad_perm:[1,0,3,2] row_mask:0xf bank_mask:0xf bound_ctrl:1
	v_add_f32_dpp v114, v114, v114 quad_perm:[1,0,3,2] row_mask:0xf bank_mask:0xf bound_ctrl:1
	v_add_f32_dpp v115, v115, v115 quad_perm:[1,0,3,2] row_mask:0xf bank_mask:0xf bound_ctrl:1
	v_add_f32_dpp v112, v112, v112 quad_perm:[2,3,0,1] row_mask:0xf bank_mask:0xf bound_ctrl:1
	v_add_f32_dpp v113, v113, v113 quad_perm:[2,3,0,1] row_mask:0xf bank_mask:0xf bound_ctrl:1
	v_add_f32_dpp v114, v114, v114 quad_perm:[2,3,0,1] row_mask:0xf bank_mask:0xf bound_ctrl:1
	v_add_f32_dpp v115, v115, v115 quad_perm:[2,3,0,1] row_mask:0xf bank_mask:0xf bound_ctrl:1
	v_add_f32_dpp v112, v112, v112 row_half_mirror row_mask:0xf bank_mask:0xf bound_ctrl:1
	v_add_f32_dpp v113, v113, v113 row_half_mirror row_mask:0xf bank_mask:0xf bound_ctrl:1
	v_add_f32_dpp v114, v114, v114 row_half_mirror row_mask:0xf bank_mask:0xf bound_ctrl:1
	v_add_f32_dpp v115, v115, v115 row_half_mirror row_mask:0xf bank_mask:0xf bound_ctrl:1
	v_add_f32_dpp v112, v112, v112 row_mirror row_mask:0xf bank_mask:0xf bound_ctrl:1
	v_add_f32_dpp v113, v113, v113 row_mirror row_mask:0xf bank_mask:0xf bound_ctrl:1
	v_add_f32_dpp v114, v114, v114 row_mirror row_mask:0xf bank_mask:0xf bound_ctrl:1
	v_add_f32_dpp v115, v115, v115 row_mirror row_mask:0xf bank_mask:0xf bound_ctrl:1
	ds_bpermute_b32 v116, v4, v112
	ds_bpermute_b32 v117, v4, v113
	ds_bpermute_b32 v118, v4, v114
	ds_bpermute_b32 v119, v4, v115
	v_mul_f32_e32 v132, 0xbfb8aa3b, v124
	v_mul_f32_e32 v133, 0xbfb8aa3b, v125
	v_mul_f32_e32 v134, 0xbfb8aa3b, v126
	v_mul_f32_e32 v135, 0xbfb8aa3b, v127
	v_mul_f32_e32 v136, 0xbfb8aa3b, v128
	v_mul_f32_e32 v137, 0xbfb8aa3b, v129
	v_mul_f32_e32 v138, 0xbfb8aa3b, v130
	v_mul_f32_e32 v139, 0xbfb8aa3b, v131
	s_waitcnt lgkmcnt(0)
	v_add_f32_e32 v112, v112, v116
	v_add_f32_e32 v113, v113, v117
	v_add_f32_e32 v114, v114, v118
	v_add_f32_e32 v115, v115, v119
	ds_bpermute_b32 v116, v5, v112
	ds_bpermute_b32 v117, v5, v113
	ds_bpermute_b32 v118, v5, v114
	ds_bpermute_b32 v119, v5, v115
	v_exp_f32_e32 v132, v132
	v_exp_f32_e32 v133, v133
	v_exp_f32_e32 v134, v134
	v_exp_f32_e32 v135, v135
	v_exp_f32_e32 v136, v136
	v_exp_f32_e32 v137, v137
	v_exp_f32_e32 v138, v138
	v_exp_f32_e32 v139, v139
	v_add_f32_e32 v132, 1.0, v132
	v_add_f32_e32 v133, 1.0, v133
	v_add_f32_e32 v134, 1.0, v134
	v_add_f32_e32 v135, 1.0, v135
	v_add_f32_e32 v136, 1.0, v136
	v_add_f32_e32 v137, 1.0, v137
	v_add_f32_e32 v138, 1.0, v138
	v_add_f32_e32 v139, 1.0, v139
	v_rcp_f32_e32 v132, v132
	v_rcp_f32_e32 v133, v133
	v_rcp_f32_e32 v134, v134
	v_rcp_f32_e32 v135, v135
	v_rcp_f32_e32 v136, v136
	v_rcp_f32_e32 v137, v137
	v_rcp_f32_e32 v138, v138
	v_rcp_f32_e32 v139, v139
	s_waitcnt lgkmcnt(0)
	v_add_f32_e32 v112, v112, v116
	v_add_f32_e32 v113, v113, v117
	v_add_f32_e32 v114, v114, v118
	v_add_f32_e32 v115, v115, v119
	v_mul_f32_e32 v124, v132, v124
	v_mul_f32_e32 v125, v133, v125
	v_mul_f32_e32 v126, v134, v126
	v_mul_f32_e32 v127, v135, v127
	v_mul_f32_e32 v128, v136, v128
	v_mul_f32_e32 v129, v137, v129
	v_mul_f32_e32 v130, v138, v130
	v_mul_f32_e32 v131, v139, v131
	v_fma_f32 v120, v112, s6, v10
	v_fma_f32 v121, v113, s6, v10
	v_fma_f32 v122, v114, s6, v10
	v_fma_f32 v123, v115, s6, v10
	v_rsq_f32_e32 v120, v120
	v_rsq_f32_e32 v121, v121
	v_rsq_f32_e32 v122, v122
	v_rsq_f32_e32 v123, v123
	s_nop 0
	v_mul_f32_e32 v28, v28, v120
	v_mul_f32_e32 v29, v29, v120
	v_mul_f32_e32 v30, v30, v121
	v_mul_f32_e32 v31, v31, v121
	v_mul_f32_e32 v32, v32, v122
	v_mul_f32_e32 v33, v33, v122
	v_mul_f32_e32 v34, v34, v123
	v_mul_f32_e32 v35, v35, v123
	v_mul_f32_e32 v28, v6, v28
	v_mul_f32_e32 v29, v7, v29
	v_mul_f32_e32 v30, v6, v30
	v_mul_f32_e32 v31, v7, v31
	v_mul_f32_e32 v32, v6, v32
	v_mul_f32_e32 v33, v7, v33
	v_mul_f32_e32 v34, v6, v34
	v_mul_f32_e32 v35, v7, v35
	v_mul_f32_e32 v28, v124, v28
	v_mul_f32_e32 v29, v125, v29
	v_mul_f32_e32 v30, v126, v30
	v_mul_f32_e32 v31, v127, v31
	v_mul_f32_e32 v32, v128, v32
	v_mul_f32_e32 v33, v129, v33
	v_mul_f32_e32 v34, v130, v34
	v_mul_f32_e32 v35, v131, v35
	v_cvt_pk_bf16_f32 v140, v28, v29
	v_cvt_pk_bf16_f32 v141, v30, v31
	v_cvt_pk_bf16_f32 v142, v32, v33
	v_cvt_pk_bf16_f32 v143, v34, v35
	global_store_dword v1, v140, s[14:15]
	global_store_dword v1, v141, s[14:15] offset:256
	global_store_dword v1, v142, s[14:15] offset:512
	global_store_dword v1, v143, s[14:15] offset:768
	s_add_u32 s14, s14, 0x400000
	s_addc_u32 s15, s15, 0
	global_load_dwordx2 v[100:101], v3, s[8:9]
	s_add_u32 s8, s8, 0x100000
	s_addc_u32 s9, s9, 0
	global_load_dwordx2 v[102:103], v3, s[8:9]
	s_add_u32 s8, s8, 0x100000
	s_addc_u32 s9, s9, 0
	global_load_dwordx2 v[104:105], v3, s[8:9]
	s_add_u32 s8, s8, 0x100000
	s_addc_u32 s9, s9, 0
	global_load_dwordx2 v[106:107], v3, s[8:9]
	s_add_u32 s8, s8, 0x100000
	s_addc_u32 s9, s9, 0
	global_load_dword v108, v1, s[12:13]
	global_load_dword v109, v1, s[12:13] offset:256
	global_load_dword v110, v1, s[12:13] offset:512
	global_load_dword v111, v1, s[12:13] offset:768
	s_add_u32 s12, s12, 0xe00000
	s_addc_u32 s13, s13, 0
	s_waitcnt vmcnt(48)
	v_mul_f32_e32 v112, v40, v40
	v_mul_f32_e32 v113, v42, v42
	v_mul_f32_e32 v114, v44, v44
	v_mul_f32_e32 v115, v46, v46
	v_fmac_f32_e32 v112, v41, v41
	v_fmac_f32_e32 v113, v43, v43
	v_fmac_f32_e32 v114, v45, v45
	v_fmac_f32_e32 v115, v47, v47
	v_lshlrev_b32_e32 v124, 16, v48
	v_and_b32_e32 v125, 0xffff0000, v48
	v_lshlrev_b32_e32 v126, 16, v49
	v_and_b32_e32 v127, 0xffff0000, v49
	v_lshlrev_b32_e32 v128, 16, v50
	v_and_b32_e32 v129, 0xffff0000, v50
	v_lshlrev_b32_e32 v130, 16, v51
	v_and_b32_e32 v131, 0xffff0000, v51
	v_add_f32_dpp v112, v112, v112 quad_perm:[1,0,3,2] row_mask:0xf bank_mask:0xf bound_ctrl:1
	v_add_f32_dpp v113, v113, v113 quad_perm:[1,0,3,2] row_mask:0xf bank_mask:0xf bound_ctrl:1
	v_add_f32_dpp v114, v114, v114 quad_perm:[1,0,3,2] row_mask:0xf bank_mask:0xf bound_ctrl:1
	v_add_f32_dpp v115, v115, v115 quad_perm:[1,0,3,2] row_mask:0xf bank_mask:0xf bound_ctrl:1
	v_add_f32_dpp v112, v112, v112 quad_perm:[2,3,0,1] row_mask:0xf bank_mask:0xf bound_ctrl:1
	v_add_f32_dpp v113, v113, v113 quad_perm:[2,3,0,1] row_mask:0xf bank_mask:0xf bound_ctrl:1
	v_add_f32_dpp v114, v114, v114 quad_perm:[2,3,0,1] row_mask:0xf bank_mask:0xf bound_ctrl:1
	v_add_f32_dpp v115, v115, v115 quad_perm:[2,3,0,1] row_mask:0xf bank_mask:0xf bound_ctrl:1
	v_add_f32_dpp v112, v112, v112 row_half_mirror row_mask:0xf bank_mask:0xf bound_ctrl:1
	v_add_f32_dpp v113, v113, v113 row_half_mirror row_mask:0xf bank_mask:0xf bound_ctrl:1
	v_add_f32_dpp v114, v114, v114 row_half_mirror row_mask:0xf bank_mask:0xf bound_ctrl:1
	v_add_f32_dpp v115, v115, v115 row_half_mirror row_mask:0xf bank_mask:0xf bound_ctrl:1
	v_add_f32_dpp v112, v112, v112 row_mirror row_mask:0xf bank_mask:0xf bound_ctrl:1
	v_add_f32_dpp v113, v113, v113 row_mirror row_mask:0xf bank_mask:0xf bound_ctrl:1
	v_add_f32_dpp v114, v114, v114 row_mirror row_mask:0xf bank_mask:0xf bound_ctrl:1
	v_add_f32_dpp v115, v115, v115 row_mirror row_mask:0xf bank_mask:0xf bound_ctrl:1
	ds_bpermute_b32 v116, v4, v112
	ds_bpermute_b32 v117, v4, v113
	ds_bpermute_b32 v118, v4, v114
	ds_bpermute_b32 v119, v4, v115
	v_mul_f32_e32 v132, 0xbfb8aa3b, v124
	v_mul_f32_e32 v133, 0xbfb8aa3b, v125
	v_mul_f32_e32 v134, 0xbfb8aa3b, v126
	v_mul_f32_e32 v135, 0xbfb8aa3b, v127
	v_mul_f32_e32 v136, 0xbfb8aa3b, v128
	v_mul_f32_e32 v137, 0xbfb8aa3b, v129
	v_mul_f32_e32 v138, 0xbfb8aa3b, v130
	v_mul_f32_e32 v139, 0xbfb8aa3b, v131
	s_waitcnt lgkmcnt(0)
	v_add_f32_e32 v112, v112, v116
	v_add_f32_e32 v113, v113, v117
	v_add_f32_e32 v114, v114, v118
	v_add_f32_e32 v115, v115, v119
	ds_bpermute_b32 v116, v5, v112
	ds_bpermute_b32 v117, v5, v113
	ds_bpermute_b32 v118, v5, v114
	ds_bpermute_b32 v119, v5, v115
	v_exp_f32_e32 v132, v132
	v_exp_f32_e32 v133, v133
	v_exp_f32_e32 v134, v134
	v_exp_f32_e32 v135, v135
	v_exp_f32_e32 v136, v136
	v_exp_f32_e32 v137, v137
	v_exp_f32_e32 v138, v138
	v_exp_f32_e32 v139, v139
	v_add_f32_e32 v132, 1.0, v132
	v_add_f32_e32 v133, 1.0, v133
	v_add_f32_e32 v134, 1.0, v134
	v_add_f32_e32 v135, 1.0, v135
	v_add_f32_e32 v136, 1.0, v136
	v_add_f32_e32 v137, 1.0, v137
	v_add_f32_e32 v138, 1.0, v138
	v_add_f32_e32 v139, 1.0, v139
	v_rcp_f32_e32 v132, v132
	v_rcp_f32_e32 v133, v133
	v_rcp_f32_e32 v134, v134
	v_rcp_f32_e32 v135, v135
	v_rcp_f32_e32 v136, v136
	v_rcp_f32_e32 v137, v137
	v_rcp_f32_e32 v138, v138
	v_rcp_f32_e32 v139, v139
	s_waitcnt lgkmcnt(0)
	v_add_f32_e32 v112, v112, v116
	v_add_f32_e32 v113, v113, v117
	v_add_f32_e32 v114, v114, v118
	v_add_f32_e32 v115, v115, v119
	v_mul_f32_e32 v124, v132, v124
	v_mul_f32_e32 v125, v133, v125
	v_mul_f32_e32 v126, v134, v126
	v_mul_f32_e32 v127, v135, v127
	v_mul_f32_e32 v128, v136, v128
	v_mul_f32_e32 v129, v137, v129
	v_mul_f32_e32 v130, v138, v130
	v_mul_f32_e32 v131, v139, v131
	v_fma_f32 v120, v112, s6, v10
	v_fma_f32 v121, v113, s6, v10
	v_fma_f32 v122, v114, s6, v10
	v_fma_f32 v123, v115, s6, v10
	v_rsq_f32_e32 v120, v120
	v_rsq_f32_e32 v121, v121
	v_rsq_f32_e32 v122, v122
	v_rsq_f32_e32 v123, v123
	s_nop 0
	v_mul_f32_e32 v40, v40, v120
	v_mul_f32_e32 v41, v41, v120
	v_mul_f32_e32 v42, v42, v121
	v_mul_f32_e32 v43, v43, v121
	v_mul_f32_e32 v44, v44, v122
	v_mul_f32_e32 v45, v45, v122
	v_mul_f32_e32 v46, v46, v123
	v_mul_f32_e32 v47, v47, v123
	v_mul_f32_e32 v40, v6, v40
	v_mul_f32_e32 v41, v7, v41
	v_mul_f32_e32 v42, v6, v42
	v_mul_f32_e32 v43, v7, v43
	v_mul_f32_e32 v44, v6, v44
	v_mul_f32_e32 v45, v7, v45
	v_mul_f32_e32 v46, v6, v46
	v_mul_f32_e32 v47, v7, v47
	v_mul_f32_e32 v40, v124, v40
	v_mul_f32_e32 v41, v125, v41
	v_mul_f32_e32 v42, v126, v42
	v_mul_f32_e32 v43, v127, v43
	v_mul_f32_e32 v44, v128, v44
	v_mul_f32_e32 v45, v129, v45
	v_mul_f32_e32 v46, v130, v46
	v_mul_f32_e32 v47, v131, v47
	v_cvt_pk_bf16_f32 v140, v40, v41
	v_cvt_pk_bf16_f32 v141, v42, v43
	v_cvt_pk_bf16_f32 v142, v44, v45
	v_cvt_pk_bf16_f32 v143, v46, v47
	global_store_dword v1, v140, s[14:15]
	global_store_dword v1, v141, s[14:15] offset:256
	global_store_dword v1, v142, s[14:15] offset:512
	global_store_dword v1, v143, s[14:15] offset:768
	s_add_u32 s14, s14, 0x400000
	s_addc_u32 s15, s15, 0
	s_waitcnt vmcnt(44)
	v_mul_f32_e32 v112, v52, v52
	v_mul_f32_e32 v113, v54, v54
	v_mul_f32_e32 v114, v56, v56
	v_mul_f32_e32 v115, v58, v58
	v_fmac_f32_e32 v112, v53, v53
	v_fmac_f32_e32 v113, v55, v55
	v_fmac_f32_e32 v114, v57, v57
	v_fmac_f32_e32 v115, v59, v59
	v_lshlrev_b32_e32 v124, 16, v60
	v_and_b32_e32 v125, 0xffff0000, v60
	v_lshlrev_b32_e32 v126, 16, v61
	v_and_b32_e32 v127, 0xffff0000, v61
	v_lshlrev_b32_e32 v128, 16, v62
	v_and_b32_e32 v129, 0xffff0000, v62
	v_lshlrev_b32_e32 v130, 16, v63
	v_and_b32_e32 v131, 0xffff0000, v63
	v_add_f32_dpp v112, v112, v112 quad_perm:[1,0,3,2] row_mask:0xf bank_mask:0xf bound_ctrl:1
	v_add_f32_dpp v113, v113, v113 quad_perm:[1,0,3,2] row_mask:0xf bank_mask:0xf bound_ctrl:1
	v_add_f32_dpp v114, v114, v114 quad_perm:[1,0,3,2] row_mask:0xf bank_mask:0xf bound_ctrl:1
	v_add_f32_dpp v115, v115, v115 quad_perm:[1,0,3,2] row_mask:0xf bank_mask:0xf bound_ctrl:1
	v_add_f32_dpp v112, v112, v112 quad_perm:[2,3,0,1] row_mask:0xf bank_mask:0xf bound_ctrl:1
	v_add_f32_dpp v113, v113, v113 quad_perm:[2,3,0,1] row_mask:0xf bank_mask:0xf bound_ctrl:1
	v_add_f32_dpp v114, v114, v114 quad_perm:[2,3,0,1] row_mask:0xf bank_mask:0xf bound_ctrl:1
	v_add_f32_dpp v115, v115, v115 quad_perm:[2,3,0,1] row_mask:0xf bank_mask:0xf bound_ctrl:1
	v_add_f32_dpp v112, v112, v112 row_half_mirror row_mask:0xf bank_mask:0xf bound_ctrl:1
	v_add_f32_dpp v113, v113, v113 row_half_mirror row_mask:0xf bank_mask:0xf bound_ctrl:1
	v_add_f32_dpp v114, v114, v114 row_half_mirror row_mask:0xf bank_mask:0xf bound_ctrl:1
	v_add_f32_dpp v115, v115, v115 row_half_mirror row_mask:0xf bank_mask:0xf bound_ctrl:1
	v_add_f32_dpp v112, v112, v112 row_mirror row_mask:0xf bank_mask:0xf bound_ctrl:1
	v_add_f32_dpp v113, v113, v113 row_mirror row_mask:0xf bank_mask:0xf bound_ctrl:1
	v_add_f32_dpp v114, v114, v114 row_mirror row_mask:0xf bank_mask:0xf bound_ctrl:1
	v_add_f32_dpp v115, v115, v115 row_mirror row_mask:0xf bank_mask:0xf bound_ctrl:1
	ds_bpermute_b32 v116, v4, v112
	ds_bpermute_b32 v117, v4, v113
	ds_bpermute_b32 v118, v4, v114
	ds_bpermute_b32 v119, v4, v115
	v_mul_f32_e32 v132, 0xbfb8aa3b, v124
	v_mul_f32_e32 v133, 0xbfb8aa3b, v125
	v_mul_f32_e32 v134, 0xbfb8aa3b, v126
	v_mul_f32_e32 v135, 0xbfb8aa3b, v127
	v_mul_f32_e32 v136, 0xbfb8aa3b, v128
	v_mul_f32_e32 v137, 0xbfb8aa3b, v129
	v_mul_f32_e32 v138, 0xbfb8aa3b, v130
	v_mul_f32_e32 v139, 0xbfb8aa3b, v131
	s_waitcnt lgkmcnt(0)
	v_add_f32_e32 v112, v112, v116
	v_add_f32_e32 v113, v113, v117
	v_add_f32_e32 v114, v114, v118
	v_add_f32_e32 v115, v115, v119
	ds_bpermute_b32 v116, v5, v112
	ds_bpermute_b32 v117, v5, v113
	ds_bpermute_b32 v118, v5, v114
	ds_bpermute_b32 v119, v5, v115
	v_exp_f32_e32 v132, v132
	v_exp_f32_e32 v133, v133
	v_exp_f32_e32 v134, v134
	v_exp_f32_e32 v135, v135
	v_exp_f32_e32 v136, v136
	v_exp_f32_e32 v137, v137
	v_exp_f32_e32 v138, v138
	v_exp_f32_e32 v139, v139
	v_add_f32_e32 v132, 1.0, v132
	v_add_f32_e32 v133, 1.0, v133
	v_add_f32_e32 v134, 1.0, v134
	v_add_f32_e32 v135, 1.0, v135
	v_add_f32_e32 v136, 1.0, v136
	v_add_f32_e32 v137, 1.0, v137
	v_add_f32_e32 v138, 1.0, v138
	v_add_f32_e32 v139, 1.0, v139
	v_rcp_f32_e32 v132, v132
	v_rcp_f32_e32 v133, v133
	v_rcp_f32_e32 v134, v134
	v_rcp_f32_e32 v135, v135
	v_rcp_f32_e32 v136, v136
	v_rcp_f32_e32 v137, v137
	v_rcp_f32_e32 v138, v138
	v_rcp_f32_e32 v139, v139
	s_waitcnt lgkmcnt(0)
	v_add_f32_e32 v112, v112, v116
	v_add_f32_e32 v113, v113, v117
	v_add_f32_e32 v114, v114, v118
	v_add_f32_e32 v115, v115, v119
	v_mul_f32_e32 v124, v132, v124
	v_mul_f32_e32 v125, v133, v125
	v_mul_f32_e32 v126, v134, v126
	v_mul_f32_e32 v127, v135, v127
	v_mul_f32_e32 v128, v136, v128
	v_mul_f32_e32 v129, v137, v129
	v_mul_f32_e32 v130, v138, v130
	v_mul_f32_e32 v131, v139, v131
	v_fma_f32 v120, v112, s6, v10
	v_fma_f32 v121, v113, s6, v10
	v_fma_f32 v122, v114, s6, v10
	v_fma_f32 v123, v115, s6, v10
	v_rsq_f32_e32 v120, v120
	v_rsq_f32_e32 v121, v121
	v_rsq_f32_e32 v122, v122
	v_rsq_f32_e32 v123, v123
	s_nop 0
	v_mul_f32_e32 v52, v52, v120
	v_mul_f32_e32 v53, v53, v120
	v_mul_f32_e32 v54, v54, v121
	v_mul_f32_e32 v55, v55, v121
	v_mul_f32_e32 v56, v56, v122
	v_mul_f32_e32 v57, v57, v122
	v_mul_f32_e32 v58, v58, v123
	v_mul_f32_e32 v59, v59, v123
	v_mul_f32_e32 v52, v6, v52
	v_mul_f32_e32 v53, v7, v53
	v_mul_f32_e32 v54, v6, v54
	v_mul_f32_e32 v55, v7, v55
	v_mul_f32_e32 v56, v6, v56
	v_mul_f32_e32 v57, v7, v57
	v_mul_f32_e32 v58, v6, v58
	v_mul_f32_e32 v59, v7, v59
	v_mul_f32_e32 v52, v124, v52
	v_mul_f32_e32 v53, v125, v53
	v_mul_f32_e32 v54, v126, v54
	v_mul_f32_e32 v55, v127, v55
	v_mul_f32_e32 v56, v128, v56
	v_mul_f32_e32 v57, v129, v57
	v_mul_f32_e32 v58, v130, v58
	v_mul_f32_e32 v59, v131, v59
	v_cvt_pk_bf16_f32 v140, v52, v53
	v_cvt_pk_bf16_f32 v141, v54, v55
	v_cvt_pk_bf16_f32 v142, v56, v57
	v_cvt_pk_bf16_f32 v143, v58, v59
	global_store_dword v1, v140, s[14:15]
	global_store_dword v1, v141, s[14:15] offset:256
	global_store_dword v1, v142, s[14:15] offset:512
	global_store_dword v1, v143, s[14:15] offset:768
	s_add_u32 s14, s14, 0x400000
	s_addc_u32 s15, s15, 0
	s_waitcnt vmcnt(40)
	v_mul_f32_e32 v112, v64, v64
	v_mul_f32_e32 v113, v66, v66
	v_mul_f32_e32 v114, v68, v68
	v_mul_f32_e32 v115, v70, v70
	v_fmac_f32_e32 v112, v65, v65
	v_fmac_f32_e32 v113, v67, v67
	v_fmac_f32_e32 v114, v69, v69
	v_fmac_f32_e32 v115, v71, v71
	v_lshlrev_b32_e32 v124, 16, v72
	v_and_b32_e32 v125, 0xffff0000, v72
	v_lshlrev_b32_e32 v126, 16, v73
	v_and_b32_e32 v127, 0xffff0000, v73
	v_lshlrev_b32_e32 v128, 16, v74
	v_and_b32_e32 v129, 0xffff0000, v74
	v_lshlrev_b32_e32 v130, 16, v75
	v_and_b32_e32 v131, 0xffff0000, v75
	v_add_f32_dpp v112, v112, v112 quad_perm:[1,0,3,2] row_mask:0xf bank_mask:0xf bound_ctrl:1
	v_add_f32_dpp v113, v113, v113 quad_perm:[1,0,3,2] row_mask:0xf bank_mask:0xf bound_ctrl:1
	v_add_f32_dpp v114, v114, v114 quad_perm:[1,0,3,2] row_mask:0xf bank_mask:0xf bound_ctrl:1
	v_add_f32_dpp v115, v115, v115 quad_perm:[1,0,3,2] row_mask:0xf bank_mask:0xf bound_ctrl:1
	v_add_f32_dpp v112, v112, v112 quad_perm:[2,3,0,1] row_mask:0xf bank_mask:0xf bound_ctrl:1
	v_add_f32_dpp v113, v113, v113 quad_perm:[2,3,0,1] row_mask:0xf bank_mask:0xf bound_ctrl:1
	v_add_f32_dpp v114, v114, v114 quad_perm:[2,3,0,1] row_mask:0xf bank_mask:0xf bound_ctrl:1
	v_add_f32_dpp v115, v115, v115 quad_perm:[2,3,0,1] row_mask:0xf bank_mask:0xf bound_ctrl:1
	v_add_f32_dpp v112, v112, v112 row_half_mirror row_mask:0xf bank_mask:0xf bound_ctrl:1
	v_add_f32_dpp v113, v113, v113 row_half_mirror row_mask:0xf bank_mask:0xf bound_ctrl:1
	v_add_f32_dpp v114, v114, v114 row_half_mirror row_mask:0xf bank_mask:0xf bound_ctrl:1
	v_add_f32_dpp v115, v115, v115 row_half_mirror row_mask:0xf bank_mask:0xf bound_ctrl:1
	v_add_f32_dpp v112, v112, v112 row_mirror row_mask:0xf bank_mask:0xf bound_ctrl:1
	v_add_f32_dpp v113, v113, v113 row_mirror row_mask:0xf bank_mask:0xf bound_ctrl:1
	v_add_f32_dpp v114, v114, v114 row_mirror row_mask:0xf bank_mask:0xf bound_ctrl:1
	v_add_f32_dpp v115, v115, v115 row_mirror row_mask:0xf bank_mask:0xf bound_ctrl:1
	ds_bpermute_b32 v116, v4, v112
	ds_bpermute_b32 v117, v4, v113
	ds_bpermute_b32 v118, v4, v114
	ds_bpermute_b32 v119, v4, v115
	v_mul_f32_e32 v132, 0xbfb8aa3b, v124
	v_mul_f32_e32 v133, 0xbfb8aa3b, v125
	v_mul_f32_e32 v134, 0xbfb8aa3b, v126
	v_mul_f32_e32 v135, 0xbfb8aa3b, v127
	v_mul_f32_e32 v136, 0xbfb8aa3b, v128
	v_mul_f32_e32 v137, 0xbfb8aa3b, v129
	v_mul_f32_e32 v138, 0xbfb8aa3b, v130
	v_mul_f32_e32 v139, 0xbfb8aa3b, v131
	s_waitcnt lgkmcnt(0)
	v_add_f32_e32 v112, v112, v116
	v_add_f32_e32 v113, v113, v117
	v_add_f32_e32 v114, v114, v118
	v_add_f32_e32 v115, v115, v119
	ds_bpermute_b32 v116, v5, v112
	ds_bpermute_b32 v117, v5, v113
	ds_bpermute_b32 v118, v5, v114
	ds_bpermute_b32 v119, v5, v115
	v_exp_f32_e32 v132, v132
	v_exp_f32_e32 v133, v133
	v_exp_f32_e32 v134, v134
	v_exp_f32_e32 v135, v135
	v_exp_f32_e32 v136, v136
	v_exp_f32_e32 v137, v137
	v_exp_f32_e32 v138, v138
	v_exp_f32_e32 v139, v139
	v_add_f32_e32 v132, 1.0, v132
	v_add_f32_e32 v133, 1.0, v133
	v_add_f32_e32 v134, 1.0, v134
	v_add_f32_e32 v135, 1.0, v135
	v_add_f32_e32 v136, 1.0, v136
	v_add_f32_e32 v137, 1.0, v137
	v_add_f32_e32 v138, 1.0, v138
	v_add_f32_e32 v139, 1.0, v139
	v_rcp_f32_e32 v132, v132
	v_rcp_f32_e32 v133, v133
	v_rcp_f32_e32 v134, v134
	v_rcp_f32_e32 v135, v135
	v_rcp_f32_e32 v136, v136
	v_rcp_f32_e32 v137, v137
	v_rcp_f32_e32 v138, v138
	v_rcp_f32_e32 v139, v139
	s_waitcnt lgkmcnt(0)
	v_add_f32_e32 v112, v112, v116
	v_add_f32_e32 v113, v113, v117
	v_add_f32_e32 v114, v114, v118
	v_add_f32_e32 v115, v115, v119
	v_mul_f32_e32 v124, v132, v124
	v_mul_f32_e32 v125, v133, v125
	v_mul_f32_e32 v126, v134, v126
	v_mul_f32_e32 v127, v135, v127
	v_mul_f32_e32 v128, v136, v128
	v_mul_f32_e32 v129, v137, v129
	v_mul_f32_e32 v130, v138, v130
	v_mul_f32_e32 v131, v139, v131
	v_fma_f32 v120, v112, s6, v10
	v_fma_f32 v121, v113, s6, v10
	v_fma_f32 v122, v114, s6, v10
	v_fma_f32 v123, v115, s6, v10
	v_rsq_f32_e32 v120, v120
	v_rsq_f32_e32 v121, v121
	v_rsq_f32_e32 v122, v122
	v_rsq_f32_e32 v123, v123
	s_nop 0
	v_mul_f32_e32 v64, v64, v120
	v_mul_f32_e32 v65, v65, v120
	v_mul_f32_e32 v66, v66, v121
	v_mul_f32_e32 v67, v67, v121
	v_mul_f32_e32 v68, v68, v122
	v_mul_f32_e32 v69, v69, v122
	v_mul_f32_e32 v70, v70, v123
	v_mul_f32_e32 v71, v71, v123
	v_mul_f32_e32 v64, v6, v64
	v_mul_f32_e32 v65, v7, v65
	v_mul_f32_e32 v66, v6, v66
	v_mul_f32_e32 v67, v7, v67
	v_mul_f32_e32 v68, v6, v68
	v_mul_f32_e32 v69, v7, v69
	v_mul_f32_e32 v70, v6, v70
	v_mul_f32_e32 v71, v7, v71
	v_mul_f32_e32 v64, v124, v64
	v_mul_f32_e32 v65, v125, v65
	v_mul_f32_e32 v66, v126, v66
	v_mul_f32_e32 v67, v127, v67
	v_mul_f32_e32 v68, v128, v68
	v_mul_f32_e32 v69, v129, v69
	v_mul_f32_e32 v70, v130, v70
	v_mul_f32_e32 v71, v131, v71
	v_cvt_pk_bf16_f32 v140, v64, v65
	v_cvt_pk_bf16_f32 v141, v66, v67
	v_cvt_pk_bf16_f32 v142, v68, v69
	v_cvt_pk_bf16_f32 v143, v70, v71
	global_store_dword v1, v140, s[14:15]
	global_store_dword v1, v141, s[14:15] offset:256
	global_store_dword v1, v142, s[14:15] offset:512
	global_store_dword v1, v143, s[14:15] offset:768
	s_add_u32 s14, s14, 0x400000
	s_addc_u32 s15, s15, 0
	s_waitcnt vmcnt(36)
	v_mul_f32_e32 v112, v76, v76
	v_mul_f32_e32 v113, v78, v78
	v_mul_f32_e32 v114, v80, v80
	v_mul_f32_e32 v115, v82, v82
	v_fmac_f32_e32 v112, v77, v77
	v_fmac_f32_e32 v113, v79, v79
	v_fmac_f32_e32 v114, v81, v81
	v_fmac_f32_e32 v115, v83, v83
	v_lshlrev_b32_e32 v124, 16, v84
	v_and_b32_e32 v125, 0xffff0000, v84
	v_lshlrev_b32_e32 v126, 16, v85
	v_and_b32_e32 v127, 0xffff0000, v85
	v_lshlrev_b32_e32 v128, 16, v86
	v_and_b32_e32 v129, 0xffff0000, v86
	v_lshlrev_b32_e32 v130, 16, v87
	v_and_b32_e32 v131, 0xffff0000, v87
	v_add_f32_dpp v112, v112, v112 quad_perm:[1,0,3,2] row_mask:0xf bank_mask:0xf bound_ctrl:1
	v_add_f32_dpp v113, v113, v113 quad_perm:[1,0,3,2] row_mask:0xf bank_mask:0xf bound_ctrl:1
	v_add_f32_dpp v114, v114, v114 quad_perm:[1,0,3,2] row_mask:0xf bank_mask:0xf bound_ctrl:1
	v_add_f32_dpp v115, v115, v115 quad_perm:[1,0,3,2] row_mask:0xf bank_mask:0xf bound_ctrl:1
	v_add_f32_dpp v112, v112, v112 quad_perm:[2,3,0,1] row_mask:0xf bank_mask:0xf bound_ctrl:1
	v_add_f32_dpp v113, v113, v113 quad_perm:[2,3,0,1] row_mask:0xf bank_mask:0xf bound_ctrl:1
	v_add_f32_dpp v114, v114, v114 quad_perm:[2,3,0,1] row_mask:0xf bank_mask:0xf bound_ctrl:1
	v_add_f32_dpp v115, v115, v115 quad_perm:[2,3,0,1] row_mask:0xf bank_mask:0xf bound_ctrl:1
	v_add_f32_dpp v112, v112, v112 row_half_mirror row_mask:0xf bank_mask:0xf bound_ctrl:1
	v_add_f32_dpp v113, v113, v113 row_half_mirror row_mask:0xf bank_mask:0xf bound_ctrl:1
	v_add_f32_dpp v114, v114, v114 row_half_mirror row_mask:0xf bank_mask:0xf bound_ctrl:1
	v_add_f32_dpp v115, v115, v115 row_half_mirror row_mask:0xf bank_mask:0xf bound_ctrl:1
	v_add_f32_dpp v112, v112, v112 row_mirror row_mask:0xf bank_mask:0xf bound_ctrl:1
	v_add_f32_dpp v113, v113, v113 row_mirror row_mask:0xf bank_mask:0xf bound_ctrl:1
	v_add_f32_dpp v114, v114, v114 row_mirror row_mask:0xf bank_mask:0xf bound_ctrl:1
	v_add_f32_dpp v115, v115, v115 row_mirror row_mask:0xf bank_mask:0xf bound_ctrl:1
	ds_bpermute_b32 v116, v4, v112
	ds_bpermute_b32 v117, v4, v113
	ds_bpermute_b32 v118, v4, v114
	ds_bpermute_b32 v119, v4, v115
	v_mul_f32_e32 v132, 0xbfb8aa3b, v124
	v_mul_f32_e32 v133, 0xbfb8aa3b, v125
	v_mul_f32_e32 v134, 0xbfb8aa3b, v126
	v_mul_f32_e32 v135, 0xbfb8aa3b, v127
	v_mul_f32_e32 v136, 0xbfb8aa3b, v128
	v_mul_f32_e32 v137, 0xbfb8aa3b, v129
	v_mul_f32_e32 v138, 0xbfb8aa3b, v130
	v_mul_f32_e32 v139, 0xbfb8aa3b, v131
	s_waitcnt lgkmcnt(0)
	v_add_f32_e32 v112, v112, v116
	v_add_f32_e32 v113, v113, v117
	v_add_f32_e32 v114, v114, v118
	v_add_f32_e32 v115, v115, v119
	ds_bpermute_b32 v116, v5, v112
	ds_bpermute_b32 v117, v5, v113
	ds_bpermute_b32 v118, v5, v114
	ds_bpermute_b32 v119, v5, v115
	v_exp_f32_e32 v132, v132
	v_exp_f32_e32 v133, v133
	v_exp_f32_e32 v134, v134
	v_exp_f32_e32 v135, v135
	v_exp_f32_e32 v136, v136
	v_exp_f32_e32 v137, v137
	v_exp_f32_e32 v138, v138
	v_exp_f32_e32 v139, v139
	v_add_f32_e32 v132, 1.0, v132
	v_add_f32_e32 v133, 1.0, v133
	v_add_f32_e32 v134, 1.0, v134
	v_add_f32_e32 v135, 1.0, v135
	v_add_f32_e32 v136, 1.0, v136
	v_add_f32_e32 v137, 1.0, v137
	v_add_f32_e32 v138, 1.0, v138
	v_add_f32_e32 v139, 1.0, v139
	v_rcp_f32_e32 v132, v132
	v_rcp_f32_e32 v133, v133
	v_rcp_f32_e32 v134, v134
	v_rcp_f32_e32 v135, v135
	v_rcp_f32_e32 v136, v136
	v_rcp_f32_e32 v137, v137
	v_rcp_f32_e32 v138, v138
	v_rcp_f32_e32 v139, v139
	s_waitcnt lgkmcnt(0)
	v_add_f32_e32 v112, v112, v116
	v_add_f32_e32 v113, v113, v117
	v_add_f32_e32 v114, v114, v118
	v_add_f32_e32 v115, v115, v119
	v_mul_f32_e32 v124, v132, v124
	v_mul_f32_e32 v125, v133, v125
	v_mul_f32_e32 v126, v134, v126
	v_mul_f32_e32 v127, v135, v127
	v_mul_f32_e32 v128, v136, v128
	v_mul_f32_e32 v129, v137, v129
	v_mul_f32_e32 v130, v138, v130
	v_mul_f32_e32 v131, v139, v131
	v_fma_f32 v120, v112, s6, v10
	v_fma_f32 v121, v113, s6, v10
	v_fma_f32 v122, v114, s6, v10
	v_fma_f32 v123, v115, s6, v10
	v_rsq_f32_e32 v120, v120
	v_rsq_f32_e32 v121, v121
	v_rsq_f32_e32 v122, v122
	v_rsq_f32_e32 v123, v123
	s_nop 0
	v_mul_f32_e32 v76, v76, v120
	v_mul_f32_e32 v77, v77, v120
	v_mul_f32_e32 v78, v78, v121
	v_mul_f32_e32 v79, v79, v121
	v_mul_f32_e32 v80, v80, v122
	v_mul_f32_e32 v81, v81, v122
	v_mul_f32_e32 v82, v82, v123
	v_mul_f32_e32 v83, v83, v123
	v_mul_f32_e32 v76, v6, v76
	v_mul_f32_e32 v77, v7, v77
	v_mul_f32_e32 v78, v6, v78
	v_mul_f32_e32 v79, v7, v79
	v_mul_f32_e32 v80, v6, v80
	v_mul_f32_e32 v81, v7, v81
	v_mul_f32_e32 v82, v6, v82
	v_mul_f32_e32 v83, v7, v83
	v_mul_f32_e32 v76, v124, v76
	v_mul_f32_e32 v77, v125, v77
	v_mul_f32_e32 v78, v126, v78
	v_mul_f32_e32 v79, v127, v79
	v_mul_f32_e32 v80, v128, v80
	v_mul_f32_e32 v81, v129, v81
	v_mul_f32_e32 v82, v130, v82
	v_mul_f32_e32 v83, v131, v83
	v_cvt_pk_bf16_f32 v140, v76, v77
	v_cvt_pk_bf16_f32 v141, v78, v79
	v_cvt_pk_bf16_f32 v142, v80, v81
	v_cvt_pk_bf16_f32 v143, v82, v83
	global_store_dword v1, v140, s[14:15]
	global_store_dword v1, v141, s[14:15] offset:256
	global_store_dword v1, v142, s[14:15] offset:512
	global_store_dword v1, v143, s[14:15] offset:768
	s_add_u32 s14, s14, 0x400000
	s_addc_u32 s15, s15, 0
	s_waitcnt vmcnt(28)
	v_mul_f32_e32 v112, v88, v88
	v_mul_f32_e32 v113, v90, v90
	v_mul_f32_e32 v114, v92, v92
	v_mul_f32_e32 v115, v94, v94
	v_fmac_f32_e32 v112, v89, v89
	v_fmac_f32_e32 v113, v91, v91
	v_fmac_f32_e32 v114, v93, v93
	v_fmac_f32_e32 v115, v95, v95
	v_lshlrev_b32_e32 v124, 16, v96
	v_and_b32_e32 v125, 0xffff0000, v96
	v_lshlrev_b32_e32 v126, 16, v97
	v_and_b32_e32 v127, 0xffff0000, v97
	v_lshlrev_b32_e32 v128, 16, v98
	v_and_b32_e32 v129, 0xffff0000, v98
	v_lshlrev_b32_e32 v130, 16, v99
	v_and_b32_e32 v131, 0xffff0000, v99
	v_add_f32_dpp v112, v112, v112 quad_perm:[1,0,3,2] row_mask:0xf bank_mask:0xf bound_ctrl:1
	v_add_f32_dpp v113, v113, v113 quad_perm:[1,0,3,2] row_mask:0xf bank_mask:0xf bound_ctrl:1
	v_add_f32_dpp v114, v114, v114 quad_perm:[1,0,3,2] row_mask:0xf bank_mask:0xf bound_ctrl:1
	v_add_f32_dpp v115, v115, v115 quad_perm:[1,0,3,2] row_mask:0xf bank_mask:0xf bound_ctrl:1
	v_add_f32_dpp v112, v112, v112 quad_perm:[2,3,0,1] row_mask:0xf bank_mask:0xf bound_ctrl:1
	v_add_f32_dpp v113, v113, v113 quad_perm:[2,3,0,1] row_mask:0xf bank_mask:0xf bound_ctrl:1
	v_add_f32_dpp v114, v114, v114 quad_perm:[2,3,0,1] row_mask:0xf bank_mask:0xf bound_ctrl:1
	v_add_f32_dpp v115, v115, v115 quad_perm:[2,3,0,1] row_mask:0xf bank_mask:0xf bound_ctrl:1
	v_add_f32_dpp v112, v112, v112 row_half_mirror row_mask:0xf bank_mask:0xf bound_ctrl:1
	v_add_f32_dpp v113, v113, v113 row_half_mirror row_mask:0xf bank_mask:0xf bound_ctrl:1
	v_add_f32_dpp v114, v114, v114 row_half_mirror row_mask:0xf bank_mask:0xf bound_ctrl:1
	v_add_f32_dpp v115, v115, v115 row_half_mirror row_mask:0xf bank_mask:0xf bound_ctrl:1
	v_add_f32_dpp v112, v112, v112 row_mirror row_mask:0xf bank_mask:0xf bound_ctrl:1
	v_add_f32_dpp v113, v113, v113 row_mirror row_mask:0xf bank_mask:0xf bound_ctrl:1
	v_add_f32_dpp v114, v114, v114 row_mirror row_mask:0xf bank_mask:0xf bound_ctrl:1
	v_add_f32_dpp v115, v115, v115 row_mirror row_mask:0xf bank_mask:0xf bound_ctrl:1
	ds_bpermute_b32 v116, v4, v112
	ds_bpermute_b32 v117, v4, v113
	ds_bpermute_b32 v118, v4, v114
	ds_bpermute_b32 v119, v4, v115
	v_mul_f32_e32 v132, 0xbfb8aa3b, v124
	v_mul_f32_e32 v133, 0xbfb8aa3b, v125
	v_mul_f32_e32 v134, 0xbfb8aa3b, v126
	v_mul_f32_e32 v135, 0xbfb8aa3b, v127
	v_mul_f32_e32 v136, 0xbfb8aa3b, v128
	v_mul_f32_e32 v137, 0xbfb8aa3b, v129
	v_mul_f32_e32 v138, 0xbfb8aa3b, v130
	v_mul_f32_e32 v139, 0xbfb8aa3b, v131
	s_waitcnt lgkmcnt(0)
	v_add_f32_e32 v112, v112, v116
	v_add_f32_e32 v113, v113, v117
	v_add_f32_e32 v114, v114, v118
	v_add_f32_e32 v115, v115, v119
	ds_bpermute_b32 v116, v5, v112
	ds_bpermute_b32 v117, v5, v113
	ds_bpermute_b32 v118, v5, v114
	ds_bpermute_b32 v119, v5, v115
	v_exp_f32_e32 v132, v132
	v_exp_f32_e32 v133, v133
	v_exp_f32_e32 v134, v134
	v_exp_f32_e32 v135, v135
	v_exp_f32_e32 v136, v136
	v_exp_f32_e32 v137, v137
	v_exp_f32_e32 v138, v138
	v_exp_f32_e32 v139, v139
	v_add_f32_e32 v132, 1.0, v132
	v_add_f32_e32 v133, 1.0, v133
	v_add_f32_e32 v134, 1.0, v134
	v_add_f32_e32 v135, 1.0, v135
	v_add_f32_e32 v136, 1.0, v136
	v_add_f32_e32 v137, 1.0, v137
	v_add_f32_e32 v138, 1.0, v138
	v_add_f32_e32 v139, 1.0, v139
	v_rcp_f32_e32 v132, v132
	v_rcp_f32_e32 v133, v133
	v_rcp_f32_e32 v134, v134
	v_rcp_f32_e32 v135, v135
	v_rcp_f32_e32 v136, v136
	v_rcp_f32_e32 v137, v137
	v_rcp_f32_e32 v138, v138
	v_rcp_f32_e32 v139, v139
	s_waitcnt lgkmcnt(0)
	v_add_f32_e32 v112, v112, v116
	v_add_f32_e32 v113, v113, v117
	v_add_f32_e32 v114, v114, v118
	v_add_f32_e32 v115, v115, v119
	v_mul_f32_e32 v124, v132, v124
	v_mul_f32_e32 v125, v133, v125
	v_mul_f32_e32 v126, v134, v126
	v_mul_f32_e32 v127, v135, v127
	v_mul_f32_e32 v128, v136, v128
	v_mul_f32_e32 v129, v137, v129
	v_mul_f32_e32 v130, v138, v130
	v_mul_f32_e32 v131, v139, v131
	v_fma_f32 v120, v112, s6, v10
	v_fma_f32 v121, v113, s6, v10
	v_fma_f32 v122, v114, s6, v10
	v_fma_f32 v123, v115, s6, v10
	v_rsq_f32_e32 v120, v120
	v_rsq_f32_e32 v121, v121
	v_rsq_f32_e32 v122, v122
	v_rsq_f32_e32 v123, v123
	s_nop 0
	v_mul_f32_e32 v88, v88, v120
	v_mul_f32_e32 v89, v89, v120
	v_mul_f32_e32 v90, v90, v121
	v_mul_f32_e32 v91, v91, v121
	v_mul_f32_e32 v92, v92, v122
	v_mul_f32_e32 v93, v93, v122
	v_mul_f32_e32 v94, v94, v123
	v_mul_f32_e32 v95, v95, v123
	v_mul_f32_e32 v88, v6, v88
	v_mul_f32_e32 v89, v7, v89
	v_mul_f32_e32 v90, v6, v90
	v_mul_f32_e32 v91, v7, v91
	v_mul_f32_e32 v92, v6, v92
	v_mul_f32_e32 v93, v7, v93
	v_mul_f32_e32 v94, v6, v94
	v_mul_f32_e32 v95, v7, v95
	v_mul_f32_e32 v88, v124, v88
	v_mul_f32_e32 v89, v125, v89
	v_mul_f32_e32 v90, v126, v90
	v_mul_f32_e32 v91, v127, v91
	v_mul_f32_e32 v92, v128, v92
	v_mul_f32_e32 v93, v129, v93
	v_mul_f32_e32 v94, v130, v94
	v_mul_f32_e32 v95, v131, v95
	v_cvt_pk_bf16_f32 v140, v88, v89
	v_cvt_pk_bf16_f32 v141, v90, v91
	v_cvt_pk_bf16_f32 v142, v92, v93
	v_cvt_pk_bf16_f32 v143, v94, v95
	global_store_dword v1, v140, s[14:15]
	global_store_dword v1, v141, s[14:15] offset:256
	global_store_dword v1, v142, s[14:15] offset:512
	global_store_dword v1, v143, s[14:15] offset:768
	s_add_u32 s14, s14, 0x400000
	s_addc_u32 s15, s15, 0
	s_waitcnt vmcnt(20)
	v_mul_f32_e32 v112, v100, v100
	v_mul_f32_e32 v113, v102, v102
	v_mul_f32_e32 v114, v104, v104
	v_mul_f32_e32 v115, v106, v106
	v_fmac_f32_e32 v112, v101, v101
	v_fmac_f32_e32 v113, v103, v103
	v_fmac_f32_e32 v114, v105, v105
	v_fmac_f32_e32 v115, v107, v107
	v_lshlrev_b32_e32 v124, 16, v108
	v_and_b32_e32 v125, 0xffff0000, v108
	v_lshlrev_b32_e32 v126, 16, v109
	v_and_b32_e32 v127, 0xffff0000, v109
	v_lshlrev_b32_e32 v128, 16, v110
	v_and_b32_e32 v129, 0xffff0000, v110
	v_lshlrev_b32_e32 v130, 16, v111
	v_and_b32_e32 v131, 0xffff0000, v111
	v_add_f32_dpp v112, v112, v112 quad_perm:[1,0,3,2] row_mask:0xf bank_mask:0xf bound_ctrl:1
	v_add_f32_dpp v113, v113, v113 quad_perm:[1,0,3,2] row_mask:0xf bank_mask:0xf bound_ctrl:1
	v_add_f32_dpp v114, v114, v114 quad_perm:[1,0,3,2] row_mask:0xf bank_mask:0xf bound_ctrl:1
	v_add_f32_dpp v115, v115, v115 quad_perm:[1,0,3,2] row_mask:0xf bank_mask:0xf bound_ctrl:1
	v_add_f32_dpp v112, v112, v112 quad_perm:[2,3,0,1] row_mask:0xf bank_mask:0xf bound_ctrl:1
	v_add_f32_dpp v113, v113, v113 quad_perm:[2,3,0,1] row_mask:0xf bank_mask:0xf bound_ctrl:1
	v_add_f32_dpp v114, v114, v114 quad_perm:[2,3,0,1] row_mask:0xf bank_mask:0xf bound_ctrl:1
	v_add_f32_dpp v115, v115, v115 quad_perm:[2,3,0,1] row_mask:0xf bank_mask:0xf bound_ctrl:1
	v_add_f32_dpp v112, v112, v112 row_half_mirror row_mask:0xf bank_mask:0xf bound_ctrl:1
	v_add_f32_dpp v113, v113, v113 row_half_mirror row_mask:0xf bank_mask:0xf bound_ctrl:1
	v_add_f32_dpp v114, v114, v114 row_half_mirror row_mask:0xf bank_mask:0xf bound_ctrl:1
	v_add_f32_dpp v115, v115, v115 row_half_mirror row_mask:0xf bank_mask:0xf bound_ctrl:1
	v_add_f32_dpp v112, v112, v112 row_mirror row_mask:0xf bank_mask:0xf bound_ctrl:1
	v_add_f32_dpp v113, v113, v113 row_mirror row_mask:0xf bank_mask:0xf bound_ctrl:1
	v_add_f32_dpp v114, v114, v114 row_mirror row_mask:0xf bank_mask:0xf bound_ctrl:1
	v_add_f32_dpp v115, v115, v115 row_mirror row_mask:0xf bank_mask:0xf bound_ctrl:1
	ds_bpermute_b32 v116, v4, v112
	ds_bpermute_b32 v117, v4, v113
	ds_bpermute_b32 v118, v4, v114
	ds_bpermute_b32 v119, v4, v115
	v_mul_f32_e32 v132, 0xbfb8aa3b, v124
	v_mul_f32_e32 v133, 0xbfb8aa3b, v125
	v_mul_f32_e32 v134, 0xbfb8aa3b, v126
	v_mul_f32_e32 v135, 0xbfb8aa3b, v127
	v_mul_f32_e32 v136, 0xbfb8aa3b, v128
	v_mul_f32_e32 v137, 0xbfb8aa3b, v129
	v_mul_f32_e32 v138, 0xbfb8aa3b, v130
	v_mul_f32_e32 v139, 0xbfb8aa3b, v131
	s_waitcnt lgkmcnt(0)
	v_add_f32_e32 v112, v112, v116
	v_add_f32_e32 v113, v113, v117
	v_add_f32_e32 v114, v114, v118
	v_add_f32_e32 v115, v115, v119
	ds_bpermute_b32 v116, v5, v112
	ds_bpermute_b32 v117, v5, v113
	ds_bpermute_b32 v118, v5, v114
	ds_bpermute_b32 v119, v5, v115
	v_exp_f32_e32 v132, v132
	v_exp_f32_e32 v133, v133
	v_exp_f32_e32 v134, v134
	v_exp_f32_e32 v135, v135
	v_exp_f32_e32 v136, v136
	v_exp_f32_e32 v137, v137
	v_exp_f32_e32 v138, v138
	v_exp_f32_e32 v139, v139
	v_add_f32_e32 v132, 1.0, v132
	v_add_f32_e32 v133, 1.0, v133
	v_add_f32_e32 v134, 1.0, v134
	v_add_f32_e32 v135, 1.0, v135
	v_add_f32_e32 v136, 1.0, v136
	v_add_f32_e32 v137, 1.0, v137
	v_add_f32_e32 v138, 1.0, v138
	v_add_f32_e32 v139, 1.0, v139
	v_rcp_f32_e32 v132, v132
	v_rcp_f32_e32 v133, v133
	v_rcp_f32_e32 v134, v134
	v_rcp_f32_e32 v135, v135
	v_rcp_f32_e32 v136, v136
	v_rcp_f32_e32 v137, v137
	v_rcp_f32_e32 v138, v138
	v_rcp_f32_e32 v139, v139
	s_waitcnt lgkmcnt(0)
	v_add_f32_e32 v112, v112, v116
	v_add_f32_e32 v113, v113, v117
	v_add_f32_e32 v114, v114, v118
	v_add_f32_e32 v115, v115, v119
	v_mul_f32_e32 v124, v132, v124
	v_mul_f32_e32 v125, v133, v125
	v_mul_f32_e32 v126, v134, v126
	v_mul_f32_e32 v127, v135, v127
	v_mul_f32_e32 v128, v136, v128
	v_mul_f32_e32 v129, v137, v129
	v_mul_f32_e32 v130, v138, v130
	v_mul_f32_e32 v131, v139, v131
	v_fma_f32 v120, v112, s6, v10
	v_fma_f32 v121, v113, s6, v10
	v_fma_f32 v122, v114, s6, v10
	v_fma_f32 v123, v115, s6, v10
	v_rsq_f32_e32 v120, v120
	v_rsq_f32_e32 v121, v121
	v_rsq_f32_e32 v122, v122
	v_rsq_f32_e32 v123, v123
	s_nop 0
	v_mul_f32_e32 v100, v100, v120
	v_mul_f32_e32 v101, v101, v120
	v_mul_f32_e32 v102, v102, v121
	v_mul_f32_e32 v103, v103, v121
	v_mul_f32_e32 v104, v104, v122
	v_mul_f32_e32 v105, v105, v122
	v_mul_f32_e32 v106, v106, v123
	v_mul_f32_e32 v107, v107, v123
	v_mul_f32_e32 v100, v6, v100
	v_mul_f32_e32 v101, v7, v101
	v_mul_f32_e32 v102, v6, v102
	v_mul_f32_e32 v103, v7, v103
	v_mul_f32_e32 v104, v6, v104
	v_mul_f32_e32 v105, v7, v105
	v_mul_f32_e32 v106, v6, v106
	v_mul_f32_e32 v107, v7, v107
	v_mul_f32_e32 v100, v124, v100
	v_mul_f32_e32 v101, v125, v101
	v_mul_f32_e32 v102, v126, v102
	v_mul_f32_e32 v103, v127, v103
	v_mul_f32_e32 v104, v128, v104
	v_mul_f32_e32 v105, v129, v105
	v_mul_f32_e32 v106, v130, v106
	v_mul_f32_e32 v107, v131, v107
	v_cvt_pk_bf16_f32 v140, v100, v101
	v_cvt_pk_bf16_f32 v141, v102, v103
	v_cvt_pk_bf16_f32 v142, v104, v105
	v_cvt_pk_bf16_f32 v143, v106, v107
	global_store_dword v1, v140, s[14:15]
	global_store_dword v1, v141, s[14:15] offset:256
	global_store_dword v1, v142, s[14:15] offset:512
	global_store_dword v1, v143, s[14:15] offset:768
	s_add_u32 s14, s14, 0x400000
	s_addc_u32 s15, s15, 0
	s_branch .LBB0_412
	s_nop 0
	s_nop 0
	s_nop 0
	s_nop 0
	s_nop 0
	s_nop 0
	s_nop 0
	s_nop 0
	s_nop 0
	s_nop 0
	s_nop 0
	s_nop 0
	s_nop 0
	s_nop 0
	s_nop 0
	s_nop 0
	s_nop 0
	s_nop 0
	s_nop 0
	s_nop 0
	s_nop 0
	s_nop 0
	s_nop 0
	s_nop 0
	s_nop 0
	s_nop 0
	s_nop 0
	s_nop 0
	s_nop 0
	s_nop 0
	s_nop 0
	s_nop 0
	s_nop 0
	s_nop 0
	s_nop 0
	s_nop 0
	s_nop 0
	s_nop 0
	s_nop 0
.Lhgn_generic:
	v_mbcnt_lo_u32_b32 v0, s6, 0
	v_mbcnt_hi_u32_b32 v6, s6, v0
	v_lshlrev_b32_e32 v7, 3, v6
	s_nop 0
	global_load_dwordx2 v[0:1], v7, s[4:5]
	v_mov_b32_e32 v3, 0
	v_lshlrev_b32_e32 v2, 2, v6
	v_lshl_add_u64 v[4:5], s[2:3], 0, v[2:3]
	v_and_b32_e32 v2, 56, v7
	v_lshlrev_b32_e32 v8, 1, v6
	v_lshrrev_b32_e32 v14, 3, v6
	v_lshl_add_u64 v[6:7], s[0:1], 0, v[2:3]
	v_mbcnt_lo_u32_b32 v2, -1, 0
	v_mbcnt_hi_u32_b32 v2, -1, v2
	v_and_b32_e32 v10, 64, v2
	v_xor_b32_e32 v9, 16, v2
	v_add_u32_e32 v10, 64, v10
	v_cmp_lt_i32_e32 vcc, v9, v10
	s_mov_b64 s[4:5], 0x2800000
	s_mov_b32 s0, 0x358637bd
	v_cndmask_b32_e32 v9, v2, v9, vcc
	v_lshlrev_b32_e32 v15, 2, v9
	v_xor_b32_e32 v9, 32, v2
	v_cmp_lt_i32_e32 vcc, v9, v10
	v_lshl_add_u64 v[4:5], v[4:5], 0, s[4:5]
	s_mov_b64 s[4:5], 0x4800c00
	v_cndmask_b32_e32 v2, v2, v9, vcc
	v_lshlrev_b32_e32 v16, 2, v2
	v_lshlrev_b32_e32 v2, 1, v8
	s_mov_b32 s11, 0x4800000
	s_mov_b32 s12, 0x100000
	s_mov_b32 s13, 0x300000
	s_mov_b32 s14, 0xffff0000
	s_brev_b32 s6, 60
	v_mov_b64_e32 v[8:9], s[0:1]
	s_mov_b32 s15, 0x800000
	s_movk_i32 s16, 0x7fff
	s_mov_b32 s8, s84
